# v69: priority window - each K-loop MFMA block keeps s_setprio 1 across all 32 MFMAs (mid-block setprio 0/1 flip removed)
# speedup vs baseline: 1.0061x; 1.0061x over previous
; #define PG8_STAGE(bufoff, gbase) do { _Pragma("unroll") for (int _i = 0; _i < 2; ++_i) \
;         __builtin_amdgcn_global_load_lds((const unsigned*)((const char*)(gbase) + voff[_i]), (LAS unsigned*)(lds + (bufoff) + ldsw + _i * 8192), 16, 0, 0); } while (0)
; #define PG8_LDA(dst, b, h) do { _Pragma("unroll") for (int m = 0; m < 4; ++m) _Pragma("unroll") for (int k = 0; k < 2; ++k) dst[m][k] = *(const LAS bf16x8*)(lds + PG8_SA(b, h) + aoff + m * 2048 + k * 1024); } while (0)
; #define PG8_LDB(dst, b, h) do { _Pragma("unroll") for (int n = 0; n < 2; ++n) _Pragma("unroll") for (int k = 0; k < 2; ++k) dst[n][k] = *(const LAS bf16x8*)(lds + PG8_SB(b, h) + boff + n * 2048 + k * 1024); } while (0)
; #define PG8_MMA(ai, bj, At, Bt) do { __builtin_amdgcn_s_setprio(1); _Pragma("unroll") for (int m = 0; m < 4; ++m) _Pragma("unroll") for (int n = 0; n < 2; ++n) _Pragma("unroll") for (int k = 0; k < 2; ++k) \
;         acc[ai][bj][m][n] = __builtin_amdgcn_mfma_f32_16x16x32_bf16(Bt[n][k], At[m][k], acc[ai][bj][m][n], 0, 0, 0); __builtin_amdgcn_s_setprio(0); } while (0)
; #define PG8_WAIT_V(n) asm volatile("s_waitcnt vmcnt(" #n ")" ::: "memory")
; #define PG8_WAIT_L(n) asm volatile("s_waitcnt lgkmcnt(" #n ")" ::: "memory")
; #define PG8_BAR __builtin_amdgcn_s_barrier()
; #define PG8_SCHED __builtin_amdgcn_sched_barrier(0)
; template <int EPI> ...
;     ...
;             PG8_LDB(B0, 0, 0); PG8_LDB(B1, 0, 1); PG8_SCHED; PG8_LDA(At, 0, 0); PG8_STAGE(PG8_SA(1, 1), a1 + hstep);
;             PG8_WAIT_V(8); PG8_WAIT_L(0); PG8_BAR; PG8_MMA(0, 0, At, B0); PG8_MMA(0, 1, At, B1); PG8_BAR; PG8_SCHED;
;             PG8_LDA(At, 0, 1); PG8_STAGE(PG8_SB(0, 0), b2); PG8_STAGE(PG8_SB(0, 1), b2 + hstep); PG8_STAGE(PG8_SA(0, 0), a2);
;             PG8_WAIT_V(8); PG8_WAIT_L(0); PG8_BAR; PG8_MMA(1, 0, At, B0); PG8_MMA(1, 1, At, B1); PG8_BAR; PG8_SCHED;
.LBB0_137:
	ds_read_b128 v[130:133], v178
	ds_read_b128 v[164:167], v178 offset:1024
	ds_read_b128 v[168:171], v178 offset:2048
	ds_read_b128 v[172:175], v178 offset:3072
	ds_read_b128 v[188:191], v179
	ds_read_b128 v[192:195], v179 offset:1024
	ds_read_b128 v[196:199], v179 offset:2048
	ds_read_b128 v[200:203], v179 offset:3072
	s_add_u32 s28, s26, 0xfffc0080
	s_addc_u32 s29, s27, -1
	s_cmp_eq_u32 s36, 12
	s_cselect_b32 s31, s5, s29
	s_cselect_b32 s30, s7, s28
	s_cselect_b32 s29, s19, s35
	s_cselect_b32 s28, s21, s34
	v_lshl_add_u64 v[176:177], s[26:27], 0, v[156:157]
	s_add_i32 m0, s42, 0xc000
	ds_read_b128 v[204:207], v180
	ds_read_b128 v[208:211], v180 offset:1024
	ds_read_b128 v[212:215], v180 offset:2048
	ds_read_b128 v[216:219], v180 offset:3072
	ds_read_b128 v[220:223], v180 offset:4096
	ds_read_b128 v[224:227], v180 offset:5120
	ds_read_b128 v[228:231], v180 offset:6144
	ds_read_b128 v[232:235], v180 offset:7168
	global_load_lds_dwordx4 v[176:177], off
	v_lshl_add_u64 v[176:177], s[26:27], 0, v[158:159]
	s_add_i32 m0, s42, 0xe000
	s_nop 0
	global_load_lds_dwordx4 v[176:177], off
	s_waitcnt vmcnt(8)
	s_waitcnt lgkmcnt(0)
	s_barrier
	s_setprio 1
	s_waitcnt lgkmcnt(0)
	v_mfma_f32_16x16x32_bf16 v[126:129], v[130:133], v[204:207], v[126:129]
	v_mfma_f32_16x16x32_bf16 v[122:125], v[168:171], v[204:207], v[122:125]
	v_mfma_f32_16x16x32_bf16 v[118:121], v[130:133], v[212:215], v[118:121]
	v_mfma_f32_16x16x32_bf16 v[114:117], v[168:171], v[212:215], v[114:117]
	v_mfma_f32_16x16x32_bf16 v[110:113], v[130:133], v[220:223], v[110:113]
	v_mfma_f32_16x16x32_bf16 v[106:109], v[168:171], v[220:223], v[106:109]
	v_mfma_f32_16x16x32_bf16 v[102:105], v[130:133], v[228:231], v[102:105]
	v_mfma_f32_16x16x32_bf16 v[98:101], v[168:171], v[228:231], v[98:101]
	v_mfma_f32_16x16x32_bf16 v[126:129], v[164:167], v[208:211], v[126:129]
	v_mfma_f32_16x16x32_bf16 v[122:125], v[172:175], v[208:211], v[122:125]
	v_mfma_f32_16x16x32_bf16 v[118:121], v[164:167], v[216:219], v[118:121]
	v_mfma_f32_16x16x32_bf16 v[114:117], v[172:175], v[216:219], v[114:117]
	v_mfma_f32_16x16x32_bf16 v[110:113], v[164:167], v[224:227], v[110:113]
	v_mfma_f32_16x16x32_bf16 v[106:109], v[172:175], v[224:227], v[106:109]
	v_mfma_f32_16x16x32_bf16 v[102:105], v[164:167], v[232:235], v[102:105]
	v_mfma_f32_16x16x32_bf16 v[98:101], v[172:175], v[232:235], v[98:101]
	v_mfma_f32_16x16x32_bf16 v[62:65], v[188:191], v[204:207], v[62:65]
	v_mfma_f32_16x16x32_bf16 v[58:61], v[196:199], v[204:207], v[58:61]
	v_mfma_f32_16x16x32_bf16 v[54:57], v[188:191], v[212:215], v[54:57]
	v_mfma_f32_16x16x32_bf16 v[50:53], v[196:199], v[212:215], v[50:53]
	v_mfma_f32_16x16x32_bf16 v[46:49], v[188:191], v[220:223], v[46:49]
	v_mfma_f32_16x16x32_bf16 v[42:45], v[196:199], v[220:223], v[42:45]
	v_mfma_f32_16x16x32_bf16 v[38:41], v[188:191], v[228:231], v[38:41]
	v_mfma_f32_16x16x32_bf16 v[34:37], v[196:199], v[228:231], v[34:37]
	v_mfma_f32_16x16x32_bf16 v[62:65], v[192:195], v[208:211], v[62:65]
	v_mfma_f32_16x16x32_bf16 v[58:61], v[200:203], v[208:211], v[58:61]
	v_mfma_f32_16x16x32_bf16 v[54:57], v[192:195], v[216:219], v[54:57]
	v_mfma_f32_16x16x32_bf16 v[50:53], v[200:203], v[216:219], v[50:53]
	v_mfma_f32_16x16x32_bf16 v[46:49], v[192:195], v[224:227], v[46:49]
	v_mfma_f32_16x16x32_bf16 v[42:45], v[200:203], v[224:227], v[42:45]
	v_mfma_f32_16x16x32_bf16 v[38:41], v[192:195], v[232:235], v[38:41]
	v_mfma_f32_16x16x32_bf16 v[34:37], v[200:203], v[232:235], v[34:37]
	s_setprio 0
	s_barrier
	s_add_i32 s37, s55, s41
	v_lshl_add_u64 v[176:177], s[28:29], 0, v[136:137]
	s_mov_b32 m0, s37
	ds_read_b128 v[204:207], v180 offset:16384
	ds_read_b128 v[208:211], v180 offset:17408
	ds_read_b128 v[212:215], v180 offset:18432
	ds_read_b128 v[216:219], v180 offset:19456
	ds_read_b128 v[220:223], v180 offset:20480
	ds_read_b128 v[224:227], v180 offset:21504
	ds_read_b128 v[228:231], v180 offset:22528
	ds_read_b128 v[232:235], v180 offset:23552
	global_load_lds_dwordx4 v[176:177], off
	s_add_i32 m0, s37, 0x2000
	s_add_u32 s38, s28, 0x40000
	v_lshl_add_u64 v[236:237], s[28:29], 0, v[138:139]
	s_addc_u32 s39, s29, 0
	s_add_i32 s37, s56, s41
	global_load_lds_dwordx4 v[236:237], off
	v_lshl_add_u64 v[238:239], s[38:39], 0, v[136:137]
	s_mov_b32 m0, s37
	v_lshl_add_u64 v[240:241], s[30:31], 0, v[138:139]
	global_load_lds_dwordx4 v[238:239], off
	v_lshl_add_u64 v[238:239], s[38:39], 0, v[138:139]
	s_add_i32 m0, s37, 0x2000
	s_nop 0
	global_load_lds_dwordx4 v[238:239], off
	v_lshl_add_u64 v[238:239], s[30:31], 0, v[136:137]
	s_mov_b32 m0, s42
	s_nop 0
	global_load_lds_dwordx4 v[238:239], off
	s_mov_b32 m0, s43
	s_nop 0
	global_load_lds_dwordx4 v[240:241], off
	s_waitcnt vmcnt(8)
	s_waitcnt lgkmcnt(0)
	s_barrier
; #define PG8_STAGE(bufoff, gbase) do { _Pragma("unroll") for (int _i = 0; _i < 2; ++_i) \
;         __builtin_amdgcn_global_load_lds((const unsigned*)((const char*)(gbase) + voff[_i]), (LAS unsigned*)(lds + (bufoff) + ldsw + _i * 8192), 16, 0, 0); } while (0)
; #define PG8_LDA(dst, b, h) do { _Pragma("unroll") for (int m = 0; m < 4; ++m) _Pragma("unroll") for (int k = 0; k < 2; ++k) dst[m][k] = *(const LAS bf16x8*)(lds + PG8_SA(b, h) + aoff + m * 2048 + k * 1024); } while (0)
; #define PG8_LDB(dst, b, h) do { _Pragma("unroll") for (int n = 0; n < 2; ++n) _Pragma("unroll") for (int k = 0; k < 2; ++k) dst[n][k] = *(const LAS bf16x8*)(lds + PG8_SB(b, h) + boff + n * 2048 + k * 1024); } while (0)
; #define PG8_MMA(ai, bj, At, Bt) do { __builtin_amdgcn_s_setprio(1); _Pragma("unroll") for (int m = 0; m < 4; ++m) _Pragma("unroll") for (int n = 0; n < 2; ++n) _Pragma("unroll") for (int k = 0; k < 2; ++k) \
;         acc[ai][bj][m][n] = __builtin_amdgcn_mfma_f32_16x16x32_bf16(Bt[n][k], At[m][k], acc[ai][bj][m][n], 0, 0, 0); __builtin_amdgcn_s_setprio(0); } while (0)
; #define PG8_WAIT_V(n) asm volatile("s_waitcnt vmcnt(" #n ")" ::: "memory")
; #define PG8_WAIT_L(n) asm volatile("s_waitcnt lgkmcnt(" #n ")" ::: "memory")
; #define PG8_BAR __builtin_amdgcn_s_barrier()
; #define PG8_SCHED __builtin_amdgcn_sched_barrier(0)
; template <int EPI> ...
;     ...
;             PG8_WAIT_V(8); PG8_WAIT_L(0); PG8_BAR; PG8_MMA(1, 0, At, B0); PG8_MMA(1, 1, At, B1); PG8_BAR; PG8_SCHED;
;             PG8_LDB(B0, 1, 0); PG8_LDB(B1, 1, 1); PG8_SCHED; PG8_LDA(At, 1, 0); PG8_STAGE(PG8_SA(0, 1), a2 + hstep);
;             PG8_WAIT_V(8); PG8_WAIT_L(0); PG8_BAR; PG8_MMA(0, 0, At, B0); PG8_MMA(0, 1, At, B1); PG8_BAR; PG8_SCHED;
	s_setprio 1
	s_waitcnt lgkmcnt(0)
	v_mfma_f32_16x16x32_bf16 v[94:97], v[130:133], v[204:207], v[94:97]
	v_mfma_f32_16x16x32_bf16 v[90:93], v[168:171], v[204:207], v[90:93]
	v_mfma_f32_16x16x32_bf16 v[86:89], v[130:133], v[212:215], v[86:89]
	v_mfma_f32_16x16x32_bf16 v[82:85], v[168:171], v[212:215], v[82:85]
	v_mfma_f32_16x16x32_bf16 v[78:81], v[130:133], v[220:223], v[78:81]
	v_mfma_f32_16x16x32_bf16 v[74:77], v[168:171], v[220:223], v[74:77]
	v_mfma_f32_16x16x32_bf16 v[70:73], v[130:133], v[228:231], v[70:73]
	v_mfma_f32_16x16x32_bf16 v[66:69], v[168:171], v[228:231], v[66:69]
	v_mfma_f32_16x16x32_bf16 v[94:97], v[164:167], v[208:211], v[94:97]
	v_mfma_f32_16x16x32_bf16 v[90:93], v[172:175], v[208:211], v[90:93]
	v_mfma_f32_16x16x32_bf16 v[86:89], v[164:167], v[216:219], v[86:89]
	v_mfma_f32_16x16x32_bf16 v[82:85], v[172:175], v[216:219], v[82:85]
	v_mfma_f32_16x16x32_bf16 v[78:81], v[164:167], v[224:227], v[78:81]
	v_mfma_f32_16x16x32_bf16 v[74:77], v[172:175], v[224:227], v[74:77]
	v_mfma_f32_16x16x32_bf16 v[70:73], v[164:167], v[232:235], v[70:73]
	v_mfma_f32_16x16x32_bf16 v[66:69], v[172:175], v[232:235], v[66:69]
	v_mfma_f32_16x16x32_bf16 v[30:33], v[188:191], v[204:207], v[30:33]
	v_mfma_f32_16x16x32_bf16 v[26:29], v[196:199], v[204:207], v[26:29]
	v_mfma_f32_16x16x32_bf16 v[22:25], v[188:191], v[212:215], v[22:25]
	v_mfma_f32_16x16x32_bf16 v[18:21], v[196:199], v[212:215], v[18:21]
	v_mfma_f32_16x16x32_bf16 v[14:17], v[188:191], v[220:223], v[14:17]
	v_mfma_f32_16x16x32_bf16 v[10:13], v[196:199], v[220:223], v[10:13]
	v_mfma_f32_16x16x32_bf16 v[6:9], v[188:191], v[228:231], v[6:9]
	v_mfma_f32_16x16x32_bf16 v[2:5], v[196:199], v[228:231], v[2:5]
	v_mfma_f32_16x16x32_bf16 v[30:33], v[192:195], v[208:211], v[30:33]
	v_mfma_f32_16x16x32_bf16 v[26:29], v[200:203], v[208:211], v[26:29]
	v_mfma_f32_16x16x32_bf16 v[22:25], v[192:195], v[216:219], v[22:25]
	v_mfma_f32_16x16x32_bf16 v[18:21], v[200:203], v[216:219], v[18:21]
	v_mfma_f32_16x16x32_bf16 v[14:17], v[192:195], v[224:227], v[14:17]
	v_mfma_f32_16x16x32_bf16 v[10:13], v[200:203], v[224:227], v[10:13]
	v_mfma_f32_16x16x32_bf16 v[6:9], v[192:195], v[232:235], v[6:9]
	v_mfma_f32_16x16x32_bf16 v[2:5], v[200:203], v[232:235], v[2:5]
	s_setprio 0
	s_barrier
	s_add_i32 s37, 0, 0x18000
	v_add_u32_e32 v140, s37, v147
	s_add_i32 s38, 0, 0x1c000
	ds_read_b128 v[130:133], v140
	ds_read_b128 v[164:167], v140 offset:1024
	ds_read_b128 v[168:171], v140 offset:2048
	ds_read_b128 v[172:175], v140 offset:3072
	v_add_u32_e32 v140, s38, v147
	ds_read_b128 v[188:191], v140
	ds_read_b128 v[192:195], v140 offset:1024
	ds_read_b128 v[196:199], v140 offset:2048
	ds_read_b128 v[200:203], v140 offset:3072
	s_add_u32 s30, s30, 0x40000
	s_addc_u32 s31, s31, 0
	s_mov_b32 m0, s44
	v_lshl_add_u64 v[242:243], s[30:31], 0, v[136:137]
	ds_read_b128 v[204:207], v180 offset:32768
	ds_read_b128 v[208:211], v180 offset:33792
	ds_read_b128 v[212:215], v180 offset:34816
	ds_read_b128 v[216:219], v180 offset:35840
	ds_read_b128 v[220:223], v180 offset:36864
	ds_read_b128 v[224:227], v180 offset:37888
	ds_read_b128 v[228:231], v180 offset:38912
	ds_read_b128 v[232:235], v180 offset:39936
	global_load_lds_dwordx4 v[242:243], off
	v_lshl_add_u64 v[242:243], s[30:31], 0, v[138:139]
	s_mov_b32 m0, s45
	s_nop 0
	global_load_lds_dwordx4 v[242:243], off
	s_waitcnt vmcnt(8)
	s_waitcnt lgkmcnt(0)
	s_barrier
	s_setprio 1
	s_waitcnt lgkmcnt(0)
	v_mfma_f32_16x16x32_bf16 v[126:129], v[130:133], v[204:207], v[126:129]
	v_mfma_f32_16x16x32_bf16 v[122:125], v[168:171], v[204:207], v[122:125]
	v_mfma_f32_16x16x32_bf16 v[118:121], v[130:133], v[212:215], v[118:121]
	v_mfma_f32_16x16x32_bf16 v[114:117], v[168:171], v[212:215], v[114:117]
	v_mfma_f32_16x16x32_bf16 v[110:113], v[130:133], v[220:223], v[110:113]
	v_mfma_f32_16x16x32_bf16 v[106:109], v[168:171], v[220:223], v[106:109]
	v_mfma_f32_16x16x32_bf16 v[102:105], v[130:133], v[228:231], v[102:105]
	v_mfma_f32_16x16x32_bf16 v[98:101], v[168:171], v[228:231], v[98:101]
	v_mfma_f32_16x16x32_bf16 v[126:129], v[164:167], v[208:211], v[126:129]
	v_mfma_f32_16x16x32_bf16 v[122:125], v[172:175], v[208:211], v[122:125]
	v_mfma_f32_16x16x32_bf16 v[118:121], v[164:167], v[216:219], v[118:121]
	v_mfma_f32_16x16x32_bf16 v[114:117], v[172:175], v[216:219], v[114:117]
	v_mfma_f32_16x16x32_bf16 v[110:113], v[164:167], v[224:227], v[110:113]
	v_mfma_f32_16x16x32_bf16 v[106:109], v[172:175], v[224:227], v[106:109]
	v_mfma_f32_16x16x32_bf16 v[102:105], v[164:167], v[232:235], v[102:105]
	v_mfma_f32_16x16x32_bf16 v[98:101], v[172:175], v[232:235], v[98:101]
	v_mfma_f32_16x16x32_bf16 v[62:65], v[188:191], v[204:207], v[62:65]
	v_mfma_f32_16x16x32_bf16 v[58:61], v[196:199], v[204:207], v[58:61]
	v_mfma_f32_16x16x32_bf16 v[54:57], v[188:191], v[212:215], v[54:57]
	v_mfma_f32_16x16x32_bf16 v[50:53], v[196:199], v[212:215], v[50:53]
	v_mfma_f32_16x16x32_bf16 v[46:49], v[188:191], v[220:223], v[46:49]
	v_mfma_f32_16x16x32_bf16 v[42:45], v[196:199], v[220:223], v[42:45]
	v_mfma_f32_16x16x32_bf16 v[38:41], v[188:191], v[228:231], v[38:41]
	v_mfma_f32_16x16x32_bf16 v[34:37], v[196:199], v[228:231], v[34:37]
	v_mfma_f32_16x16x32_bf16 v[62:65], v[192:195], v[208:211], v[62:65]
	v_mfma_f32_16x16x32_bf16 v[58:61], v[200:203], v[208:211], v[58:61]
	v_mfma_f32_16x16x32_bf16 v[54:57], v[192:195], v[216:219], v[54:57]
	v_mfma_f32_16x16x32_bf16 v[50:53], v[200:203], v[216:219], v[50:53]
	v_mfma_f32_16x16x32_bf16 v[46:49], v[192:195], v[224:227], v[46:49]
	v_mfma_f32_16x16x32_bf16 v[42:45], v[200:203], v[224:227], v[42:45]
	v_mfma_f32_16x16x32_bf16 v[38:41], v[192:195], v[232:235], v[38:41]
	v_mfma_f32_16x16x32_bf16 v[34:37], v[200:203], v[232:235], v[34:37]
	s_setprio 0
	s_barrier
; #define PG8_STAGE(bufoff, gbase) do { _Pragma("unroll") for (int _i = 0; _i < 2; ++_i) \
;         __builtin_amdgcn_global_load_lds((const unsigned*)((const char*)(gbase) + voff[_i]), (LAS unsigned*)(lds + (bufoff) + ldsw + _i * 8192), 16, 0, 0); } while (0)
; #define PG8_LDA(dst, b, h) do { _Pragma("unroll") for (int m = 0; m < 4; ++m) _Pragma("unroll") for (int k = 0; k < 2; ++k) dst[m][k] = *(const LAS bf16x8*)(lds + PG8_SA(b, h) + aoff + m * 2048 + k * 1024); } while (0)
; #define PG8_MMA(ai, bj, At, Bt) do { __builtin_amdgcn_s_setprio(1); _Pragma("unroll") for (int m = 0; m < 4; ++m) _Pragma("unroll") for (int n = 0; n < 2; ++n) _Pragma("unroll") for (int k = 0; k < 2; ++k) \
;         acc[ai][bj][m][n] = __builtin_amdgcn_mfma_f32_16x16x32_bf16(Bt[n][k], At[m][k], acc[ai][bj][m][n], 0, 0, 0); __builtin_amdgcn_s_setprio(0); } while (0)
; #define PG8_WAIT_V(n) asm volatile("s_waitcnt vmcnt(" #n ")" ::: "memory")
; #define PG8_WAIT_L(n) asm volatile("s_waitcnt lgkmcnt(" #n ")" ::: "memory")
; #define PG8_BAR __builtin_amdgcn_s_barrier()
; #define PG8_SCHED __builtin_amdgcn_sched_barrier(0)
; template <int EPI> ...
;     ...
;             PG8_LDA(At, 1, 1); PG8_STAGE(PG8_SB(1, 0), b3); PG8_STAGE(PG8_SB(1, 1), b3 + hstep); PG8_STAGE(PG8_SA(1, 0), a3);
;             PG8_WAIT_V(8); PG8_WAIT_L(0); PG8_BAR; PG8_MMA(1, 0, At, B0); PG8_MMA(1, 1, At, B1); PG8_BAR; PG8_SCHED;
;         }
	s_add_i32 s30, s37, s41
	v_lshl_add_u64 v[176:177], v[176:177], 0, s[10:11]
	s_mov_b32 m0, s30
	ds_read_b128 v[204:207], v180 offset:49152
	ds_read_b128 v[208:211], v180 offset:50176
	ds_read_b128 v[212:215], v180 offset:51200
	ds_read_b128 v[216:219], v180 offset:52224
	ds_read_b128 v[220:223], v180 offset:53248
	ds_read_b128 v[224:227], v180 offset:54272
	ds_read_b128 v[228:231], v180 offset:55296
	ds_read_b128 v[232:235], v180 offset:56320
	global_load_lds_dwordx4 v[176:177], off
	s_add_i32 m0, s30, 0x2000
	s_add_u32 s28, s28, 0x40080
	v_lshl_add_u64 v[176:177], v[236:237], 0, s[10:11]
	s_addc_u32 s29, s29, 0
	s_add_i32 s30, s38, s41
	global_load_lds_dwordx4 v[176:177], off
	v_lshl_add_u64 v[176:177], s[28:29], 0, v[136:137]
	s_mov_b32 m0, s30
	s_nop 0
	global_load_lds_dwordx4 v[176:177], off
	v_lshl_add_u64 v[176:177], s[28:29], 0, v[138:139]
	s_add_i32 m0, s30, 0x2000
	s_nop 0
	global_load_lds_dwordx4 v[176:177], off
	v_lshl_add_u64 v[176:177], v[238:239], 0, s[10:11]
	s_mov_b32 m0, s48
	s_nop 0
	global_load_lds_dwordx4 v[176:177], off
	v_lshl_add_u64 v[176:177], v[240:241], 0, s[10:11]
	s_mov_b32 m0, s49
	s_nop 0
	global_load_lds_dwordx4 v[176:177], off
	s_waitcnt vmcnt(8)
	s_waitcnt lgkmcnt(0)
	s_barrier
	s_setprio 1
	s_waitcnt lgkmcnt(0)
	v_mfma_f32_16x16x32_bf16 v[94:97], v[130:133], v[204:207], v[94:97]
	v_mfma_f32_16x16x32_bf16 v[90:93], v[168:171], v[204:207], v[90:93]
	v_mfma_f32_16x16x32_bf16 v[86:89], v[130:133], v[212:215], v[86:89]
	v_mfma_f32_16x16x32_bf16 v[82:85], v[168:171], v[212:215], v[82:85]
	v_mfma_f32_16x16x32_bf16 v[78:81], v[130:133], v[220:223], v[78:81]
	v_mfma_f32_16x16x32_bf16 v[74:77], v[168:171], v[220:223], v[74:77]
	v_mfma_f32_16x16x32_bf16 v[70:73], v[130:133], v[228:231], v[70:73]
	v_mfma_f32_16x16x32_bf16 v[66:69], v[168:171], v[228:231], v[66:69]
	v_mfma_f32_16x16x32_bf16 v[94:97], v[164:167], v[208:211], v[94:97]
	v_mfma_f32_16x16x32_bf16 v[90:93], v[172:175], v[208:211], v[90:93]
	v_mfma_f32_16x16x32_bf16 v[86:89], v[164:167], v[216:219], v[86:89]
	v_mfma_f32_16x16x32_bf16 v[82:85], v[172:175], v[216:219], v[82:85]
	v_mfma_f32_16x16x32_bf16 v[78:81], v[164:167], v[224:227], v[78:81]
	v_mfma_f32_16x16x32_bf16 v[74:77], v[172:175], v[224:227], v[74:77]
	v_mfma_f32_16x16x32_bf16 v[70:73], v[164:167], v[232:235], v[70:73]
	v_mfma_f32_16x16x32_bf16 v[66:69], v[172:175], v[232:235], v[66:69]
	v_mfma_f32_16x16x32_bf16 v[30:33], v[188:191], v[204:207], v[30:33]
	v_mfma_f32_16x16x32_bf16 v[26:29], v[196:199], v[204:207], v[26:29]
	v_mfma_f32_16x16x32_bf16 v[22:25], v[188:191], v[212:215], v[22:25]
	v_mfma_f32_16x16x32_bf16 v[18:21], v[196:199], v[212:215], v[18:21]
	v_mfma_f32_16x16x32_bf16 v[14:17], v[188:191], v[220:223], v[14:17]
	v_mfma_f32_16x16x32_bf16 v[10:13], v[196:199], v[220:223], v[10:13]
	v_mfma_f32_16x16x32_bf16 v[6:9], v[188:191], v[228:231], v[6:9]
	v_mfma_f32_16x16x32_bf16 v[2:5], v[196:199], v[228:231], v[2:5]
	v_mfma_f32_16x16x32_bf16 v[30:33], v[192:195], v[208:211], v[30:33]
	v_mfma_f32_16x16x32_bf16 v[26:29], v[200:203], v[208:211], v[26:29]
	v_mfma_f32_16x16x32_bf16 v[22:25], v[192:195], v[216:219], v[22:25]
	v_mfma_f32_16x16x32_bf16 v[18:21], v[200:203], v[216:219], v[18:21]
	v_mfma_f32_16x16x32_bf16 v[14:17], v[192:195], v[224:227], v[14:17]
	v_mfma_f32_16x16x32_bf16 v[10:13], v[200:203], v[224:227], v[10:13]
	v_mfma_f32_16x16x32_bf16 v[6:9], v[192:195], v[232:235], v[6:9]
	v_mfma_f32_16x16x32_bf16 v[2:5], v[200:203], v[232:235], v[2:5]
	s_setprio 0
	s_barrier
	s_add_i32 s36, s36, 2
	s_add_u32 s26, s26, 0x100
	s_addc_u32 s27, s27, 0
	s_add_u32 s34, s34, 0x100
	s_addc_u32 s35, s35, 0
	s_cmp_gt_u32 s36, 13
	s_cbranch_scc0 .LBB0_137
	s_and_b64 vcc, exec, s[12:13]
	s_cbranch_vccz .LBB0_140
	s_barrier

; #define PG8_STAGE(bufoff, gbase) do { _Pragma("unroll") for (int _i = 0; _i < 2; ++_i) \
;         __builtin_amdgcn_global_load_lds((const unsigned*)((const char*)(gbase) + voff[_i]), (LAS unsigned*)(lds + (bufoff) + ldsw + _i * 8192), 16, 0, 0); } while (0)
; #define PG8_LDA(dst, b, h) do { _Pragma("unroll") for (int m = 0; m < 4; ++m) _Pragma("unroll") for (int k = 0; k < 2; ++k) dst[m][k] = *(const LAS bf16x8*)(lds + PG8_SA(b, h) + aoff + m * 2048 + k * 1024); } while (0)
; #define PG8_LDB(dst, b, h) do { _Pragma("unroll") for (int n = 0; n < 2; ++n) _Pragma("unroll") for (int k = 0; k < 2; ++k) dst[n][k] = *(const LAS bf16x8*)(lds + PG8_SB(b, h) + boff + n * 2048 + k * 1024); } while (0)
; #define PG8_MMA(ai, bj, At, Bt) do { __builtin_amdgcn_s_setprio(1); _Pragma("unroll") for (int m = 0; m < 4; ++m) _Pragma("unroll") for (int n = 0; n < 2; ++n) _Pragma("unroll") for (int k = 0; k < 2; ++k) \
;         acc[ai][bj][m][n] = __builtin_amdgcn_mfma_f32_16x16x32_bf16(Bt[n][k], At[m][k], acc[ai][bj][m][n], 0, 0, 0); __builtin_amdgcn_s_setprio(0); } while (0)
; #define PG8_WAIT_V(n) asm volatile("s_waitcnt vmcnt(" #n ")" ::: "memory")
; #define PG8_WAIT_L(n) asm volatile("s_waitcnt lgkmcnt(" #n ")" ::: "memory")
; #define PG8_BAR __builtin_amdgcn_s_barrier()
; #define PG8_SCHED __builtin_amdgcn_sched_barrier(0)
; template <int EPI> ...
;     ...
;             PG8_LDB(B0, 0, 0); PG8_LDB(B1, 0, 1); PG8_SCHED; PG8_LDA(At, 0, 0); PG8_STAGE(PG8_SA(1, 1), a1 + hstep);
;             PG8_WAIT_V(8); PG8_WAIT_L(0); PG8_BAR; PG8_MMA(0, 0, At, B0); PG8_MMA(0, 1, At, B1); PG8_BAR; PG8_SCHED;
;             PG8_LDA(At, 0, 1); PG8_STAGE(PG8_SB(0, 0), b2); PG8_STAGE(PG8_SB(0, 1), b2 + hstep); PG8_STAGE(PG8_SA(0, 0), a2);
;             PG8_WAIT_V(8); PG8_WAIT_L(0); PG8_BAR; PG8_MMA(1, 0, At, B0); PG8_MMA(1, 1, At, B1); PG8_BAR; PG8_SCHED;
.LBB0_656:
	ds_read_b128 v[142:145], v158
	ds_read_b128 v[146:149], v158 offset:1024
	ds_read_b128 v[162:165], v158 offset:2048
	ds_read_b128 v[166:169], v158 offset:3072
	ds_read_b128 v[170:173], v159
	ds_read_b128 v[174:177], v159 offset:1024
	ds_read_b128 v[178:181], v159 offset:2048
	ds_read_b128 v[188:191], v159 offset:3072
	s_add_i32 s63, s62, 2
	s_add_u32 s28, s26, 0xfffe0080
	s_addc_u32 s29, s27, -1
	s_cmp_eq_u32 s59, s62
	s_cselect_b32 s31, s5, s29
	s_cselect_b32 s30, s19, s28
	s_cselect_b32 s29, s17, s61
	s_cselect_b32 s28, s58, s60
	v_lshl_add_u64 v[224:225], s[26:27], 0, v[136:137]
	s_add_i32 m0, s7, 0xc000
	ds_read_b128 v[192:195], v160
	ds_read_b128 v[196:199], v160 offset:1024
	ds_read_b128 v[200:203], v160 offset:2048
	ds_read_b128 v[204:207], v160 offset:3072
	ds_read_b128 v[208:211], v160 offset:4096
	ds_read_b128 v[212:215], v160 offset:5120
	ds_read_b128 v[216:219], v160 offset:6144
	ds_read_b128 v[220:223], v160 offset:7168
	global_load_lds_dwordx4 v[224:225], off
	v_lshl_add_u64 v[224:225], s[26:27], 0, v[138:139]
	s_add_i32 m0, s7, 0xe000
	s_nop 0
	global_load_lds_dwordx4 v[224:225], off
	s_waitcnt vmcnt(8)
	s_waitcnt lgkmcnt(0)
	s_barrier
	s_setprio 1
	s_waitcnt lgkmcnt(0)
	v_mfma_f32_16x16x32_bf16 v[126:129], v[142:145], v[192:195], v[126:129]
	v_mfma_f32_16x16x32_bf16 v[122:125], v[162:165], v[192:195], v[122:125]
	v_mfma_f32_16x16x32_bf16 v[118:121], v[142:145], v[200:203], v[118:121]
	v_mfma_f32_16x16x32_bf16 v[114:117], v[162:165], v[200:203], v[114:117]
	v_mfma_f32_16x16x32_bf16 v[106:109], v[142:145], v[208:211], v[106:109]
	v_mfma_f32_16x16x32_bf16 v[98:101], v[162:165], v[208:211], v[98:101]
	v_mfma_f32_16x16x32_bf16 v[90:93], v[142:145], v[216:219], v[90:93]
	v_mfma_f32_16x16x32_bf16 v[82:85], v[162:165], v[216:219], v[82:85]
	v_mfma_f32_16x16x32_bf16 v[126:129], v[146:149], v[196:199], v[126:129]
	v_mfma_f32_16x16x32_bf16 v[122:125], v[166:169], v[196:199], v[122:125]
	v_mfma_f32_16x16x32_bf16 v[118:121], v[146:149], v[204:207], v[118:121]
	v_mfma_f32_16x16x32_bf16 v[114:117], v[166:169], v[204:207], v[114:117]
	v_mfma_f32_16x16x32_bf16 v[106:109], v[146:149], v[212:215], v[106:109]
	v_mfma_f32_16x16x32_bf16 v[98:101], v[166:169], v[212:215], v[98:101]
	v_mfma_f32_16x16x32_bf16 v[90:93], v[146:149], v[220:223], v[90:93]
	v_mfma_f32_16x16x32_bf16 v[82:85], v[166:169], v[220:223], v[82:85]
	v_mfma_f32_16x16x32_bf16 v[110:113], v[170:173], v[192:195], v[110:113]
	v_mfma_f32_16x16x32_bf16 v[102:105], v[178:181], v[192:195], v[102:105]
	v_mfma_f32_16x16x32_bf16 v[94:97], v[170:173], v[200:203], v[94:97]
	v_mfma_f32_16x16x32_bf16 v[86:89], v[178:181], v[200:203], v[86:89]
	v_mfma_f32_16x16x32_bf16 v[78:81], v[170:173], v[208:211], v[78:81]
	v_mfma_f32_16x16x32_bf16 v[74:77], v[178:181], v[208:211], v[74:77]
	v_mfma_f32_16x16x32_bf16 v[70:73], v[170:173], v[216:219], v[70:73]
	v_mfma_f32_16x16x32_bf16 v[66:69], v[178:181], v[216:219], v[66:69]
	v_mfma_f32_16x16x32_bf16 v[110:113], v[174:177], v[196:199], v[110:113]
	v_mfma_f32_16x16x32_bf16 v[102:105], v[188:191], v[196:199], v[102:105]
	v_mfma_f32_16x16x32_bf16 v[94:97], v[174:177], v[204:207], v[94:97]
	v_mfma_f32_16x16x32_bf16 v[86:89], v[188:191], v[204:207], v[86:89]
	v_mfma_f32_16x16x32_bf16 v[78:81], v[174:177], v[212:215], v[78:81]
	v_mfma_f32_16x16x32_bf16 v[74:77], v[188:191], v[212:215], v[74:77]
	v_mfma_f32_16x16x32_bf16 v[70:73], v[174:177], v[220:223], v[70:73]
	v_mfma_f32_16x16x32_bf16 v[66:69], v[188:191], v[220:223], v[66:69]
	s_setprio 0
	s_barrier
	s_add_i32 s62, s48, s40
	v_lshl_add_u64 v[224:225], s[28:29], 0, v[130:131]
	s_mov_b32 m0, s62
	ds_read_b128 v[192:195], v160 offset:16384
	ds_read_b128 v[196:199], v160 offset:17408
	ds_read_b128 v[200:203], v160 offset:18432
	ds_read_b128 v[204:207], v160 offset:19456
	ds_read_b128 v[208:211], v160 offset:20480
	ds_read_b128 v[212:215], v160 offset:21504
	ds_read_b128 v[216:219], v160 offset:22528
	ds_read_b128 v[220:223], v160 offset:23552
	global_load_lds_dwordx4 v[224:225], off
	s_add_i32 m0, s62, 0x2000
	s_add_u32 s64, s28, 0x20000
	v_lshl_add_u64 v[226:227], s[28:29], 0, v[132:133]
	s_addc_u32 s65, s29, 0
	s_add_i32 s62, s49, s40
	global_load_lds_dwordx4 v[226:227], off
	v_lshl_add_u64 v[228:229], s[64:65], 0, v[130:131]
	s_mov_b32 m0, s62
	v_lshl_add_u64 v[230:231], s[30:31], 0, v[132:133]
	global_load_lds_dwordx4 v[228:229], off
	v_lshl_add_u64 v[228:229], s[64:65], 0, v[132:133]
	s_add_i32 m0, s62, 0x2000
	s_nop 0
	global_load_lds_dwordx4 v[228:229], off
	v_lshl_add_u64 v[228:229], s[30:31], 0, v[130:131]
	s_mov_b32 m0, s7
	s_nop 0
	global_load_lds_dwordx4 v[228:229], off
	s_mov_b32 m0, s42
	s_nop 0
	global_load_lds_dwordx4 v[230:231], off
	s_waitcnt vmcnt(8)
	s_waitcnt lgkmcnt(0)
	s_barrier
; #define PG8_STAGE(bufoff, gbase) do { _Pragma("unroll") for (int _i = 0; _i < 2; ++_i) \
;         __builtin_amdgcn_global_load_lds((const unsigned*)((const char*)(gbase) + voff[_i]), (LAS unsigned*)(lds + (bufoff) + ldsw + _i * 8192), 16, 0, 0); } while (0)
; #define PG8_LDA(dst, b, h) do { _Pragma("unroll") for (int m = 0; m < 4; ++m) _Pragma("unroll") for (int k = 0; k < 2; ++k) dst[m][k] = *(const LAS bf16x8*)(lds + PG8_SA(b, h) + aoff + m * 2048 + k * 1024); } while (0)
; #define PG8_LDB(dst, b, h) do { _Pragma("unroll") for (int n = 0; n < 2; ++n) _Pragma("unroll") for (int k = 0; k < 2; ++k) dst[n][k] = *(const LAS bf16x8*)(lds + PG8_SB(b, h) + boff + n * 2048 + k * 1024); } while (0)
; #define PG8_MMA(ai, bj, At, Bt) do { __builtin_amdgcn_s_setprio(1); _Pragma("unroll") for (int m = 0; m < 4; ++m) _Pragma("unroll") for (int n = 0; n < 2; ++n) _Pragma("unroll") for (int k = 0; k < 2; ++k) \
;         acc[ai][bj][m][n] = __builtin_amdgcn_mfma_f32_16x16x32_bf16(Bt[n][k], At[m][k], acc[ai][bj][m][n], 0, 0, 0); __builtin_amdgcn_s_setprio(0); } while (0)
; #define PG8_WAIT_V(n) asm volatile("s_waitcnt vmcnt(" #n ")" ::: "memory")
; #define PG8_WAIT_L(n) asm volatile("s_waitcnt lgkmcnt(" #n ")" ::: "memory")
; #define PG8_BAR __builtin_amdgcn_s_barrier()
; #define PG8_SCHED __builtin_amdgcn_sched_barrier(0)
; template <int EPI> ...
;     ...
;             PG8_WAIT_V(8); PG8_WAIT_L(0); PG8_BAR; PG8_MMA(1, 0, At, B0); PG8_MMA(1, 1, At, B1); PG8_BAR; PG8_SCHED;
;             PG8_LDB(B0, 1, 0); PG8_LDB(B1, 1, 1); PG8_SCHED; PG8_LDA(At, 1, 0); PG8_STAGE(PG8_SA(0, 1), a2 + hstep);
;             PG8_WAIT_V(8); PG8_WAIT_L(0); PG8_BAR; PG8_MMA(0, 0, At, B0); PG8_MMA(0, 1, At, B1); PG8_BAR; PG8_SCHED;
	s_setprio 1
	s_waitcnt lgkmcnt(0)
	v_mfma_f32_16x16x32_bf16 v[62:65], v[142:145], v[192:195], v[62:65]
	v_mfma_f32_16x16x32_bf16 v[58:61], v[162:165], v[192:195], v[58:61]
	v_mfma_f32_16x16x32_bf16 v[54:57], v[142:145], v[200:203], v[54:57]
	v_mfma_f32_16x16x32_bf16 v[50:53], v[162:165], v[200:203], v[50:53]
	v_mfma_f32_16x16x32_bf16 v[42:45], v[142:145], v[208:211], v[42:45]
	v_mfma_f32_16x16x32_bf16 v[34:37], v[162:165], v[208:211], v[34:37]
	v_mfma_f32_16x16x32_bf16 v[26:29], v[142:145], v[216:219], v[26:29]
	v_mfma_f32_16x16x32_bf16 v[18:21], v[162:165], v[216:219], v[18:21]
	v_mfma_f32_16x16x32_bf16 v[62:65], v[146:149], v[196:199], v[62:65]
	v_mfma_f32_16x16x32_bf16 v[58:61], v[166:169], v[196:199], v[58:61]
	v_mfma_f32_16x16x32_bf16 v[54:57], v[146:149], v[204:207], v[54:57]
	v_mfma_f32_16x16x32_bf16 v[50:53], v[166:169], v[204:207], v[50:53]
	v_mfma_f32_16x16x32_bf16 v[42:45], v[146:149], v[212:215], v[42:45]
	v_mfma_f32_16x16x32_bf16 v[34:37], v[166:169], v[212:215], v[34:37]
	v_mfma_f32_16x16x32_bf16 v[26:29], v[146:149], v[220:223], v[26:29]
	v_mfma_f32_16x16x32_bf16 v[18:21], v[166:169], v[220:223], v[18:21]
	v_mfma_f32_16x16x32_bf16 v[46:49], v[170:173], v[192:195], v[46:49]
	v_mfma_f32_16x16x32_bf16 v[38:41], v[178:181], v[192:195], v[38:41]
	v_mfma_f32_16x16x32_bf16 v[30:33], v[170:173], v[200:203], v[30:33]
	v_mfma_f32_16x16x32_bf16 v[22:25], v[178:181], v[200:203], v[22:25]
	v_mfma_f32_16x16x32_bf16 v[14:17], v[170:173], v[208:211], v[14:17]
	v_mfma_f32_16x16x32_bf16 v[10:13], v[178:181], v[208:211], v[10:13]
	v_mfma_f32_16x16x32_bf16 v[6:9], v[170:173], v[216:219], v[6:9]
	v_mfma_f32_16x16x32_bf16 v[2:5], v[178:181], v[216:219], v[2:5]
	v_mfma_f32_16x16x32_bf16 v[46:49], v[174:177], v[196:199], v[46:49]
	v_mfma_f32_16x16x32_bf16 v[38:41], v[188:191], v[196:199], v[38:41]
	v_mfma_f32_16x16x32_bf16 v[30:33], v[174:177], v[204:207], v[30:33]
	v_mfma_f32_16x16x32_bf16 v[22:25], v[188:191], v[204:207], v[22:25]
	v_mfma_f32_16x16x32_bf16 v[14:17], v[174:177], v[212:215], v[14:17]
	v_mfma_f32_16x16x32_bf16 v[10:13], v[188:191], v[212:215], v[10:13]
	v_mfma_f32_16x16x32_bf16 v[6:9], v[174:177], v[220:223], v[6:9]
	v_mfma_f32_16x16x32_bf16 v[2:5], v[188:191], v[220:223], v[2:5]
	s_setprio 0
	s_barrier
	s_add_i32 s62, 0, 0x18000
	v_add_u32_e32 v134, s62, v152
	s_add_i32 s64, 0, 0x1c000
	ds_read_b128 v[142:145], v134
	ds_read_b128 v[146:149], v134 offset:1024
	ds_read_b128 v[162:165], v134 offset:2048
	ds_read_b128 v[166:169], v134 offset:3072
	v_add_u32_e32 v134, s64, v152
	ds_read_b128 v[170:173], v134
	ds_read_b128 v[174:177], v134 offset:1024
	ds_read_b128 v[178:181], v134 offset:2048
	ds_read_b128 v[188:191], v134 offset:3072
	s_add_u32 s30, s30, 0x20000
	s_addc_u32 s31, s31, 0
	s_mov_b32 m0, s43
	v_lshl_add_u64 v[232:233], s[30:31], 0, v[130:131]
	ds_read_b128 v[192:195], v160 offset:32768
	ds_read_b128 v[196:199], v160 offset:33792
	ds_read_b128 v[200:203], v160 offset:34816
	ds_read_b128 v[204:207], v160 offset:35840
	ds_read_b128 v[208:211], v160 offset:36864
	ds_read_b128 v[212:215], v160 offset:37888
	ds_read_b128 v[216:219], v160 offset:38912
	ds_read_b128 v[220:223], v160 offset:39936
	global_load_lds_dwordx4 v[232:233], off
	v_lshl_add_u64 v[232:233], s[30:31], 0, v[132:133]
	s_mov_b32 m0, s44
	s_nop 0
	global_load_lds_dwordx4 v[232:233], off
	s_waitcnt vmcnt(8)
	s_waitcnt lgkmcnt(0)
	s_barrier
	s_setprio 1
	s_waitcnt lgkmcnt(0)
	v_mfma_f32_16x16x32_bf16 v[126:129], v[142:145], v[192:195], v[126:129]
	v_mfma_f32_16x16x32_bf16 v[122:125], v[162:165], v[192:195], v[122:125]
	v_mfma_f32_16x16x32_bf16 v[118:121], v[142:145], v[200:203], v[118:121]
	v_mfma_f32_16x16x32_bf16 v[114:117], v[162:165], v[200:203], v[114:117]
	v_mfma_f32_16x16x32_bf16 v[106:109], v[142:145], v[208:211], v[106:109]
	v_mfma_f32_16x16x32_bf16 v[98:101], v[162:165], v[208:211], v[98:101]
	v_mfma_f32_16x16x32_bf16 v[90:93], v[142:145], v[216:219], v[90:93]
	v_mfma_f32_16x16x32_bf16 v[82:85], v[162:165], v[216:219], v[82:85]
	v_mfma_f32_16x16x32_bf16 v[126:129], v[146:149], v[196:199], v[126:129]
	v_mfma_f32_16x16x32_bf16 v[122:125], v[166:169], v[196:199], v[122:125]
	v_mfma_f32_16x16x32_bf16 v[118:121], v[146:149], v[204:207], v[118:121]
	v_mfma_f32_16x16x32_bf16 v[114:117], v[166:169], v[204:207], v[114:117]
	v_mfma_f32_16x16x32_bf16 v[106:109], v[146:149], v[212:215], v[106:109]
	v_mfma_f32_16x16x32_bf16 v[98:101], v[166:169], v[212:215], v[98:101]
	v_mfma_f32_16x16x32_bf16 v[90:93], v[146:149], v[220:223], v[90:93]
	v_mfma_f32_16x16x32_bf16 v[82:85], v[166:169], v[220:223], v[82:85]
	v_mfma_f32_16x16x32_bf16 v[110:113], v[170:173], v[192:195], v[110:113]
	v_mfma_f32_16x16x32_bf16 v[102:105], v[178:181], v[192:195], v[102:105]
	v_mfma_f32_16x16x32_bf16 v[94:97], v[170:173], v[200:203], v[94:97]
	v_mfma_f32_16x16x32_bf16 v[86:89], v[178:181], v[200:203], v[86:89]
	v_mfma_f32_16x16x32_bf16 v[78:81], v[170:173], v[208:211], v[78:81]
	v_mfma_f32_16x16x32_bf16 v[74:77], v[178:181], v[208:211], v[74:77]
	v_mfma_f32_16x16x32_bf16 v[70:73], v[170:173], v[216:219], v[70:73]
	v_mfma_f32_16x16x32_bf16 v[66:69], v[178:181], v[216:219], v[66:69]
	v_mfma_f32_16x16x32_bf16 v[110:113], v[174:177], v[196:199], v[110:113]
	v_mfma_f32_16x16x32_bf16 v[102:105], v[188:191], v[196:199], v[102:105]
	v_mfma_f32_16x16x32_bf16 v[94:97], v[174:177], v[204:207], v[94:97]
	v_mfma_f32_16x16x32_bf16 v[86:89], v[188:191], v[204:207], v[86:89]
	v_mfma_f32_16x16x32_bf16 v[78:81], v[174:177], v[212:215], v[78:81]
	v_mfma_f32_16x16x32_bf16 v[74:77], v[188:191], v[212:215], v[74:77]
	v_mfma_f32_16x16x32_bf16 v[70:73], v[174:177], v[220:223], v[70:73]
	v_mfma_f32_16x16x32_bf16 v[66:69], v[188:191], v[220:223], v[66:69]
	s_setprio 0
	s_barrier
; #define PG8_STAGE(bufoff, gbase) do { _Pragma("unroll") for (int _i = 0; _i < 2; ++_i) \
;         __builtin_amdgcn_global_load_lds((const unsigned*)((const char*)(gbase) + voff[_i]), (LAS unsigned*)(lds + (bufoff) + ldsw + _i * 8192), 16, 0, 0); } while (0)
; #define PG8_LDA(dst, b, h) do { _Pragma("unroll") for (int m = 0; m < 4; ++m) _Pragma("unroll") for (int k = 0; k < 2; ++k) dst[m][k] = *(const LAS bf16x8*)(lds + PG8_SA(b, h) + aoff + m * 2048 + k * 1024); } while (0)
; #define PG8_MMA(ai, bj, At, Bt) do { __builtin_amdgcn_s_setprio(1); _Pragma("unroll") for (int m = 0; m < 4; ++m) _Pragma("unroll") for (int n = 0; n < 2; ++n) _Pragma("unroll") for (int k = 0; k < 2; ++k) \
;         acc[ai][bj][m][n] = __builtin_amdgcn_mfma_f32_16x16x32_bf16(Bt[n][k], At[m][k], acc[ai][bj][m][n], 0, 0, 0); __builtin_amdgcn_s_setprio(0); } while (0)
; #define PG8_WAIT_V(n) asm volatile("s_waitcnt vmcnt(" #n ")" ::: "memory")
; #define PG8_WAIT_L(n) asm volatile("s_waitcnt lgkmcnt(" #n ")" ::: "memory")
; #define PG8_BAR __builtin_amdgcn_s_barrier()
; #define PG8_SCHED __builtin_amdgcn_sched_barrier(0)
; template <int EPI> ...
;     ...
;             PG8_LDA(At, 1, 1); PG8_STAGE(PG8_SB(1, 0), b3); PG8_STAGE(PG8_SB(1, 1), b3 + hstep); PG8_STAGE(PG8_SA(1, 0), a3);
;             PG8_WAIT_V(8); PG8_WAIT_L(0); PG8_BAR; PG8_MMA(1, 0, At, B0); PG8_MMA(1, 1, At, B1); PG8_BAR; PG8_SCHED;
;         }
;         if (wr == 0) PG8_BAR;
;         if (SPLIT && cur_slice >= 0) {
	s_add_i32 s30, s62, s40
	v_lshl_add_u64 v[224:225], v[224:225], 0, s[10:11]
	s_mov_b32 m0, s30
	ds_read_b128 v[192:195], v160 offset:49152
	ds_read_b128 v[196:199], v160 offset:50176
	ds_read_b128 v[200:203], v160 offset:51200
	ds_read_b128 v[204:207], v160 offset:52224
	ds_read_b128 v[208:211], v160 offset:53248
	ds_read_b128 v[212:215], v160 offset:54272
	ds_read_b128 v[216:219], v160 offset:55296
	ds_read_b128 v[220:223], v160 offset:56320
	global_load_lds_dwordx4 v[224:225], off
	s_add_i32 m0, s30, 0x2000
	s_add_u32 s28, s28, 0x20080
	v_lshl_add_u64 v[224:225], v[226:227], 0, s[10:11]
	s_addc_u32 s29, s29, 0
	s_add_i32 s30, s64, s40
	global_load_lds_dwordx4 v[224:225], off
	v_lshl_add_u64 v[224:225], s[28:29], 0, v[130:131]
	s_mov_b32 m0, s30
	s_nop 0
	global_load_lds_dwordx4 v[224:225], off
	v_lshl_add_u64 v[224:225], s[28:29], 0, v[132:133]
	s_add_i32 m0, s30, 0x2000
	s_nop 0
	global_load_lds_dwordx4 v[224:225], off
	v_lshl_add_u64 v[224:225], v[228:229], 0, s[10:11]
	s_mov_b32 m0, s45
	s_nop 0
	global_load_lds_dwordx4 v[224:225], off
	v_lshl_add_u64 v[224:225], v[230:231], 0, s[10:11]
	s_mov_b32 m0, s46
	s_nop 0
	global_load_lds_dwordx4 v[224:225], off
	s_waitcnt vmcnt(8)
	s_waitcnt lgkmcnt(0)
	s_barrier
	s_setprio 1
	s_waitcnt lgkmcnt(0)
	v_mfma_f32_16x16x32_bf16 v[62:65], v[142:145], v[192:195], v[62:65]
	v_mfma_f32_16x16x32_bf16 v[58:61], v[162:165], v[192:195], v[58:61]
	v_mfma_f32_16x16x32_bf16 v[54:57], v[142:145], v[200:203], v[54:57]
	v_mfma_f32_16x16x32_bf16 v[50:53], v[162:165], v[200:203], v[50:53]
	v_mfma_f32_16x16x32_bf16 v[42:45], v[142:145], v[208:211], v[42:45]
	v_mfma_f32_16x16x32_bf16 v[34:37], v[162:165], v[208:211], v[34:37]
	v_mfma_f32_16x16x32_bf16 v[26:29], v[142:145], v[216:219], v[26:29]
	v_mfma_f32_16x16x32_bf16 v[18:21], v[162:165], v[216:219], v[18:21]
	v_mfma_f32_16x16x32_bf16 v[62:65], v[146:149], v[196:199], v[62:65]
	v_mfma_f32_16x16x32_bf16 v[58:61], v[166:169], v[196:199], v[58:61]
	v_mfma_f32_16x16x32_bf16 v[54:57], v[146:149], v[204:207], v[54:57]
	v_mfma_f32_16x16x32_bf16 v[50:53], v[166:169], v[204:207], v[50:53]
	v_mfma_f32_16x16x32_bf16 v[42:45], v[146:149], v[212:215], v[42:45]
	v_mfma_f32_16x16x32_bf16 v[34:37], v[166:169], v[212:215], v[34:37]
	v_mfma_f32_16x16x32_bf16 v[26:29], v[146:149], v[220:223], v[26:29]
	v_mfma_f32_16x16x32_bf16 v[18:21], v[166:169], v[220:223], v[18:21]
	v_mfma_f32_16x16x32_bf16 v[46:49], v[170:173], v[192:195], v[46:49]
	v_mfma_f32_16x16x32_bf16 v[38:41], v[178:181], v[192:195], v[38:41]
	v_mfma_f32_16x16x32_bf16 v[30:33], v[170:173], v[200:203], v[30:33]
	v_mfma_f32_16x16x32_bf16 v[22:25], v[178:181], v[200:203], v[22:25]
	v_mfma_f32_16x16x32_bf16 v[14:17], v[170:173], v[208:211], v[14:17]
	v_mfma_f32_16x16x32_bf16 v[10:13], v[178:181], v[208:211], v[10:13]
	v_mfma_f32_16x16x32_bf16 v[6:9], v[170:173], v[216:219], v[6:9]
	v_mfma_f32_16x16x32_bf16 v[2:5], v[178:181], v[216:219], v[2:5]
	v_mfma_f32_16x16x32_bf16 v[46:49], v[174:177], v[196:199], v[46:49]
	v_mfma_f32_16x16x32_bf16 v[38:41], v[188:191], v[196:199], v[38:41]
	v_mfma_f32_16x16x32_bf16 v[30:33], v[174:177], v[204:207], v[30:33]
	v_mfma_f32_16x16x32_bf16 v[22:25], v[188:191], v[204:207], v[22:25]
	v_mfma_f32_16x16x32_bf16 v[14:17], v[174:177], v[212:215], v[14:17]
	v_mfma_f32_16x16x32_bf16 v[10:13], v[188:191], v[212:215], v[10:13]
	v_mfma_f32_16x16x32_bf16 v[6:9], v[174:177], v[220:223], v[6:9]
	v_mfma_f32_16x16x32_bf16 v[2:5], v[188:191], v[220:223], v[2:5]
	s_setprio 0
	s_barrier
	s_add_u32 s26, s26, 0x100
	s_addc_u32 s27, s27, 0
	s_add_u32 s60, s60, 0x100
	s_addc_u32 s61, s61, 0
	s_cmp_ge_u32 s63, s57
	s_mov_b32 s62, s63
	s_cbranch_scc0 .LBB0_656
	s_and_b64 vcc, exec, s[12:13]
	s_cbranch_vccz .LBB0_661
	s_barrier
	s_cmp_lt_i32 s0, 0
	s_mov_b64 s[26:27], -1
	s_cbranch_scc1 .LBB0_662

; #define PG8_STAGE(bufoff, gbase) do { _Pragma("unroll") for (int _i = 0; _i < 2; ++_i) \
;         __builtin_amdgcn_global_load_lds((const unsigned*)((const char*)(gbase) + voff[_i]), (LAS unsigned*)(lds + (bufoff) + ldsw + _i * 8192), 16, 0, 0); } while (0)
; #define PG8_LDA(dst, b, h) do { _Pragma("unroll") for (int m = 0; m < 4; ++m) _Pragma("unroll") for (int k = 0; k < 2; ++k) dst[m][k] = *(const LAS bf16x8*)(lds + PG8_SA(b, h) + aoff + m * 2048 + k * 1024); } while (0)
; #define PG8_LDB(dst, b, h) do { _Pragma("unroll") for (int n = 0; n < 2; ++n) _Pragma("unroll") for (int k = 0; k < 2; ++k) dst[n][k] = *(const LAS bf16x8*)(lds + PG8_SB(b, h) + boff + n * 2048 + k * 1024); } while (0)
; #define PG8_MMA(ai, bj, At, Bt) do { __builtin_amdgcn_s_setprio(1); _Pragma("unroll") for (int m = 0; m < 4; ++m) _Pragma("unroll") for (int n = 0; n < 2; ++n) _Pragma("unroll") for (int k = 0; k < 2; ++k) \
;         acc[ai][bj][m][n] = __builtin_amdgcn_mfma_f32_16x16x32_bf16(Bt[n][k], At[m][k], acc[ai][bj][m][n], 0, 0, 0); __builtin_amdgcn_s_setprio(0); } while (0)
; #define PG8_WAIT_V(n) asm volatile("s_waitcnt vmcnt(" #n ")" ::: "memory")
; #define PG8_WAIT_L(n) asm volatile("s_waitcnt lgkmcnt(" #n ")" ::: "memory")
; #define PG8_BAR __builtin_amdgcn_s_barrier()
; #define PG8_SCHED __builtin_amdgcn_sched_barrier(0)
; template <int EPI> ...
;     ...
;         for (int t = 0; t < cnk; t += 2) {
;             const bool last = (t == cnk - 2);
;             const char* a1 = cA + (size_t)(t + 1) * kstep;
;             const char* a2 = last ? nA : cA + (size_t)(t + 2) * kstep; const char* b2 = last ? nB : cB + (size_t)(t + 2) * kstep;
;             const char* a3 = a2 + kstep; const char* b3 = b2 + kstep;
;             PG8_LDB(B0, 0, 0); PG8_LDB(B1, 0, 1); PG8_SCHED; PG8_LDA(At, 0, 0); PG8_STAGE(PG8_SA(1, 1), a1 + hstep);
;             PG8_WAIT_V(8); PG8_WAIT_L(0); PG8_BAR; PG8_MMA(0, 0, At, B0); PG8_MMA(0, 1, At, B1); PG8_BAR; PG8_SCHED;
;             PG8_LDA(At, 0, 1); PG8_STAGE(PG8_SB(0, 0), b2); PG8_STAGE(PG8_SB(0, 1), b2 + hstep); PG8_STAGE(PG8_SA(0, 0), a2);
;             PG8_WAIT_V(8); PG8_WAIT_L(0); PG8_BAR; PG8_MMA(1, 0, At, B0); PG8_MMA(1, 1, At, B1); PG8_BAR; PG8_SCHED;
.LBB0_737:
	ds_read_b128 v[142:145], v153
	ds_read_b128 v[146:149], v153 offset:1024
	ds_read_b128 v[156:159], v153 offset:2048
	ds_read_b128 v[160:163], v153 offset:3072
	ds_read_b128 v[164:167], v154
	ds_read_b128 v[168:171], v154 offset:1024
	ds_read_b128 v[172:175], v154 offset:2048
	ds_read_b128 v[176:179], v154 offset:3072
	s_add_u32 s26, s24, 0xfffe0080
	s_addc_u32 s27, s25, -1
	s_cmp_eq_u32 s52, 4
	s_cselect_b32 s29, s17, s27
	s_cselect_b32 s28, s48, s26
	s_cselect_b32 s27, s15, s51
	s_cselect_b32 s26, s49, s50
	v_lshl_add_u64 v[180:181], s[24:25], 0, v[134:135]
	s_add_i32 m0, s23, 0xc000
	ds_read_b128 v[188:191], v155
	ds_read_b128 v[192:195], v155 offset:1024
	ds_read_b128 v[196:199], v155 offset:2048
	ds_read_b128 v[200:203], v155 offset:3072
	ds_read_b128 v[204:207], v155 offset:4096
	ds_read_b128 v[208:211], v155 offset:5120
	ds_read_b128 v[212:215], v155 offset:6144
	ds_read_b128 v[216:219], v155 offset:7168
	global_load_lds_dwordx4 v[180:181], off
	v_lshl_add_u64 v[180:181], s[24:25], 0, v[136:137]
	s_add_i32 m0, s23, 0xe000
	s_nop 0
	global_load_lds_dwordx4 v[180:181], off
	s_waitcnt vmcnt(8)
	s_waitcnt lgkmcnt(0)
	s_barrier
	s_setprio 1
	s_waitcnt lgkmcnt(0)
	v_mfma_f32_16x16x32_bf16 v[126:129], v[142:145], v[188:191], v[126:129]
	v_mfma_f32_16x16x32_bf16 v[122:125], v[156:159], v[188:191], v[122:125]
	v_mfma_f32_16x16x32_bf16 v[110:113], v[142:145], v[196:199], v[110:113]
	v_mfma_f32_16x16x32_bf16 v[106:109], v[156:159], v[196:199], v[106:109]
	v_mfma_f32_16x16x32_bf16 v[94:97], v[142:145], v[204:207], v[94:97]
	v_mfma_f32_16x16x32_bf16 v[90:93], v[156:159], v[204:207], v[90:93]
	v_mfma_f32_16x16x32_bf16 v[78:81], v[142:145], v[212:215], v[78:81]
	v_mfma_f32_16x16x32_bf16 v[74:77], v[156:159], v[212:215], v[74:77]
	v_mfma_f32_16x16x32_bf16 v[126:129], v[146:149], v[192:195], v[126:129]
	v_mfma_f32_16x16x32_bf16 v[122:125], v[160:163], v[192:195], v[122:125]
	v_mfma_f32_16x16x32_bf16 v[110:113], v[146:149], v[200:203], v[110:113]
	v_mfma_f32_16x16x32_bf16 v[106:109], v[160:163], v[200:203], v[106:109]
	v_mfma_f32_16x16x32_bf16 v[94:97], v[146:149], v[208:211], v[94:97]
	v_mfma_f32_16x16x32_bf16 v[90:93], v[160:163], v[208:211], v[90:93]
	v_mfma_f32_16x16x32_bf16 v[78:81], v[146:149], v[216:219], v[78:81]
	v_mfma_f32_16x16x32_bf16 v[74:77], v[160:163], v[216:219], v[74:77]
	v_mfma_f32_16x16x32_bf16 v[118:121], v[164:167], v[188:191], v[118:121]
	v_mfma_f32_16x16x32_bf16 v[114:117], v[172:175], v[188:191], v[114:117]
	v_mfma_f32_16x16x32_bf16 v[102:105], v[164:167], v[196:199], v[102:105]
	v_mfma_f32_16x16x32_bf16 v[98:101], v[172:175], v[196:199], v[98:101]
	v_mfma_f32_16x16x32_bf16 v[86:89], v[164:167], v[204:207], v[86:89]
	v_mfma_f32_16x16x32_bf16 v[82:85], v[172:175], v[204:207], v[82:85]
	v_mfma_f32_16x16x32_bf16 v[70:73], v[164:167], v[212:215], v[70:73]
	v_mfma_f32_16x16x32_bf16 v[66:69], v[172:175], v[212:215], v[66:69]
	v_mfma_f32_16x16x32_bf16 v[118:121], v[168:171], v[192:195], v[118:121]
	v_mfma_f32_16x16x32_bf16 v[114:117], v[176:179], v[192:195], v[114:117]
	v_mfma_f32_16x16x32_bf16 v[102:105], v[168:171], v[200:203], v[102:105]
	v_mfma_f32_16x16x32_bf16 v[98:101], v[176:179], v[200:203], v[98:101]
	v_mfma_f32_16x16x32_bf16 v[86:89], v[168:171], v[208:211], v[86:89]
	v_mfma_f32_16x16x32_bf16 v[82:85], v[176:179], v[208:211], v[82:85]
	v_mfma_f32_16x16x32_bf16 v[70:73], v[168:171], v[216:219], v[70:73]
	v_mfma_f32_16x16x32_bf16 v[66:69], v[176:179], v[216:219], v[66:69]
	s_setprio 0
	s_barrier
	s_add_i32 s53, s44, s30
	v_lshl_add_u64 v[180:181], s[26:27], 0, v[130:131]
	s_mov_b32 m0, s53
	ds_read_b128 v[188:191], v155 offset:16384
	ds_read_b128 v[192:195], v155 offset:17408
	ds_read_b128 v[196:199], v155 offset:18432
	ds_read_b128 v[200:203], v155 offset:19456
	ds_read_b128 v[204:207], v155 offset:20480
	ds_read_b128 v[208:211], v155 offset:21504
	ds_read_b128 v[212:215], v155 offset:22528
	ds_read_b128 v[216:219], v155 offset:23552
	global_load_lds_dwordx4 v[180:181], off
	s_add_i32 m0, s53, 0x2000
	s_add_u32 s54, s26, 0x20000
	v_lshl_add_u64 v[220:221], s[26:27], 0, v[132:133]
	s_addc_u32 s55, s27, 0
	s_add_i32 s53, s45, s30
	global_load_lds_dwordx4 v[220:221], off
	v_lshl_add_u64 v[222:223], s[54:55], 0, v[130:131]
	s_mov_b32 m0, s53
	v_lshl_add_u64 v[224:225], s[28:29], 0, v[132:133]
	global_load_lds_dwordx4 v[222:223], off
	v_lshl_add_u64 v[222:223], s[54:55], 0, v[132:133]
	s_add_i32 m0, s53, 0x2000
	s_nop 0
	global_load_lds_dwordx4 v[222:223], off
	v_lshl_add_u64 v[222:223], s[28:29], 0, v[130:131]
	s_mov_b32 m0, s23
	s_nop 0
	global_load_lds_dwordx4 v[222:223], off
	s_mov_b32 m0, s31
	s_nop 0
	global_load_lds_dwordx4 v[224:225], off
	s_waitcnt vmcnt(8)
	s_waitcnt lgkmcnt(0)
	s_barrier
; #define PG8_STAGE(bufoff, gbase) do { _Pragma("unroll") for (int _i = 0; _i < 2; ++_i) \
;         __builtin_amdgcn_global_load_lds((const unsigned*)((const char*)(gbase) + voff[_i]), (LAS unsigned*)(lds + (bufoff) + ldsw + _i * 8192), 16, 0, 0); } while (0)
; #define PG8_LDA(dst, b, h) do { _Pragma("unroll") for (int m = 0; m < 4; ++m) _Pragma("unroll") for (int k = 0; k < 2; ++k) dst[m][k] = *(const LAS bf16x8*)(lds + PG8_SA(b, h) + aoff + m * 2048 + k * 1024); } while (0)
; #define PG8_LDB(dst, b, h) do { _Pragma("unroll") for (int n = 0; n < 2; ++n) _Pragma("unroll") for (int k = 0; k < 2; ++k) dst[n][k] = *(const LAS bf16x8*)(lds + PG8_SB(b, h) + boff + n * 2048 + k * 1024); } while (0)
; #define PG8_MMA(ai, bj, At, Bt) do { __builtin_amdgcn_s_setprio(1); _Pragma("unroll") for (int m = 0; m < 4; ++m) _Pragma("unroll") for (int n = 0; n < 2; ++n) _Pragma("unroll") for (int k = 0; k < 2; ++k) \
;         acc[ai][bj][m][n] = __builtin_amdgcn_mfma_f32_16x16x32_bf16(Bt[n][k], At[m][k], acc[ai][bj][m][n], 0, 0, 0); __builtin_amdgcn_s_setprio(0); } while (0)
; #define PG8_WAIT_V(n) asm volatile("s_waitcnt vmcnt(" #n ")" ::: "memory")
; #define PG8_WAIT_L(n) asm volatile("s_waitcnt lgkmcnt(" #n ")" ::: "memory")
; #define PG8_BAR __builtin_amdgcn_s_barrier()
; #define PG8_SCHED __builtin_amdgcn_sched_barrier(0)
; template <int EPI> ...
;     ...
;             PG8_WAIT_V(8); PG8_WAIT_L(0); PG8_BAR; PG8_MMA(1, 0, At, B0); PG8_MMA(1, 1, At, B1); PG8_BAR; PG8_SCHED;
;             PG8_LDB(B0, 1, 0); PG8_LDB(B1, 1, 1); PG8_SCHED; PG8_LDA(At, 1, 0); PG8_STAGE(PG8_SA(0, 1), a2 + hstep);
;             PG8_WAIT_V(8); PG8_WAIT_L(0); PG8_BAR; PG8_MMA(0, 0, At, B0); PG8_MMA(0, 1, At, B1); PG8_BAR; PG8_SCHED;
	s_setprio 1
	s_waitcnt lgkmcnt(0)
	v_mfma_f32_16x16x32_bf16 v[62:65], v[142:145], v[188:191], v[62:65]
	v_mfma_f32_16x16x32_bf16 v[58:61], v[156:159], v[188:191], v[58:61]
	v_mfma_f32_16x16x32_bf16 v[46:49], v[142:145], v[196:199], v[46:49]
	v_mfma_f32_16x16x32_bf16 v[42:45], v[156:159], v[196:199], v[42:45]
	v_mfma_f32_16x16x32_bf16 v[30:33], v[142:145], v[204:207], v[30:33]
	v_mfma_f32_16x16x32_bf16 v[26:29], v[156:159], v[204:207], v[26:29]
	v_mfma_f32_16x16x32_bf16 v[14:17], v[142:145], v[212:215], v[14:17]
	v_mfma_f32_16x16x32_bf16 v[10:13], v[156:159], v[212:215], v[10:13]
	v_mfma_f32_16x16x32_bf16 v[62:65], v[146:149], v[192:195], v[62:65]
	v_mfma_f32_16x16x32_bf16 v[58:61], v[160:163], v[192:195], v[58:61]
	v_mfma_f32_16x16x32_bf16 v[46:49], v[146:149], v[200:203], v[46:49]
	v_mfma_f32_16x16x32_bf16 v[42:45], v[160:163], v[200:203], v[42:45]
	v_mfma_f32_16x16x32_bf16 v[30:33], v[146:149], v[208:211], v[30:33]
	v_mfma_f32_16x16x32_bf16 v[26:29], v[160:163], v[208:211], v[26:29]
	v_mfma_f32_16x16x32_bf16 v[14:17], v[146:149], v[216:219], v[14:17]
	v_mfma_f32_16x16x32_bf16 v[10:13], v[160:163], v[216:219], v[10:13]
	v_mfma_f32_16x16x32_bf16 v[54:57], v[164:167], v[188:191], v[54:57]
	v_mfma_f32_16x16x32_bf16 v[50:53], v[172:175], v[188:191], v[50:53]
	v_mfma_f32_16x16x32_bf16 v[38:41], v[164:167], v[196:199], v[38:41]
	v_mfma_f32_16x16x32_bf16 v[34:37], v[172:175], v[196:199], v[34:37]
	v_mfma_f32_16x16x32_bf16 v[22:25], v[164:167], v[204:207], v[22:25]
	v_mfma_f32_16x16x32_bf16 v[18:21], v[172:175], v[204:207], v[18:21]
	v_mfma_f32_16x16x32_bf16 v[6:9], v[164:167], v[212:215], v[6:9]
	v_mfma_f32_16x16x32_bf16 v[2:5], v[172:175], v[212:215], v[2:5]
	v_mfma_f32_16x16x32_bf16 v[54:57], v[168:171], v[192:195], v[54:57]
	v_mfma_f32_16x16x32_bf16 v[50:53], v[176:179], v[192:195], v[50:53]
	v_mfma_f32_16x16x32_bf16 v[38:41], v[168:171], v[200:203], v[38:41]
	v_mfma_f32_16x16x32_bf16 v[34:37], v[176:179], v[200:203], v[34:37]
	v_mfma_f32_16x16x32_bf16 v[22:25], v[168:171], v[208:211], v[22:25]
	v_mfma_f32_16x16x32_bf16 v[18:21], v[176:179], v[208:211], v[18:21]
	v_mfma_f32_16x16x32_bf16 v[6:9], v[168:171], v[216:219], v[6:9]
	v_mfma_f32_16x16x32_bf16 v[2:5], v[176:179], v[216:219], v[2:5]
	s_setprio 0
	s_barrier
	s_add_i32 s53, 0, 0x18000
	s_add_i32 s54, 0, 0x1c000
	v_add_u32_e32 v160, s53, v151
	v_add_u32_e32 v176, s54, v151
	ds_read_b128 v[142:145], v160
	ds_read_b128 v[146:149], v160 offset:1024
	ds_read_b128 v[156:159], v160 offset:2048
	ds_read_b128 v[160:163], v160 offset:3072
	ds_read_b128 v[164:167], v176
	ds_read_b128 v[168:171], v176 offset:1024
	ds_read_b128 v[172:175], v176 offset:2048
	ds_read_b128 v[176:179], v176 offset:3072
	s_add_u32 s28, s28, 0x20000
	s_addc_u32 s29, s29, 0
	s_mov_b32 m0, s38
	v_lshl_add_u64 v[226:227], s[28:29], 0, v[130:131]
	ds_read_b128 v[188:191], v155 offset:32768
	ds_read_b128 v[192:195], v155 offset:33792
	ds_read_b128 v[196:199], v155 offset:34816
	ds_read_b128 v[200:203], v155 offset:35840
	ds_read_b128 v[204:207], v155 offset:36864
	ds_read_b128 v[208:211], v155 offset:37888
	ds_read_b128 v[212:215], v155 offset:38912
	ds_read_b128 v[216:219], v155 offset:39936
	global_load_lds_dwordx4 v[226:227], off
	v_lshl_add_u64 v[226:227], s[28:29], 0, v[132:133]
	s_mov_b32 m0, s39
	s_nop 0
	global_load_lds_dwordx4 v[226:227], off
	s_waitcnt vmcnt(8)
	s_waitcnt lgkmcnt(0)
	s_barrier
	s_setprio 1
	s_waitcnt lgkmcnt(0)
	v_mfma_f32_16x16x32_bf16 v[126:129], v[142:145], v[188:191], v[126:129]
	v_mfma_f32_16x16x32_bf16 v[122:125], v[156:159], v[188:191], v[122:125]
	v_mfma_f32_16x16x32_bf16 v[110:113], v[142:145], v[196:199], v[110:113]
	v_mfma_f32_16x16x32_bf16 v[106:109], v[156:159], v[196:199], v[106:109]
	v_mfma_f32_16x16x32_bf16 v[94:97], v[142:145], v[204:207], v[94:97]
	v_mfma_f32_16x16x32_bf16 v[90:93], v[156:159], v[204:207], v[90:93]
	v_mfma_f32_16x16x32_bf16 v[78:81], v[142:145], v[212:215], v[78:81]
	v_mfma_f32_16x16x32_bf16 v[74:77], v[156:159], v[212:215], v[74:77]
	v_mfma_f32_16x16x32_bf16 v[126:129], v[146:149], v[192:195], v[126:129]
	v_mfma_f32_16x16x32_bf16 v[122:125], v[160:163], v[192:195], v[122:125]
	v_mfma_f32_16x16x32_bf16 v[110:113], v[146:149], v[200:203], v[110:113]
	v_mfma_f32_16x16x32_bf16 v[106:109], v[160:163], v[200:203], v[106:109]
	v_mfma_f32_16x16x32_bf16 v[94:97], v[146:149], v[208:211], v[94:97]
	v_mfma_f32_16x16x32_bf16 v[90:93], v[160:163], v[208:211], v[90:93]
	v_mfma_f32_16x16x32_bf16 v[78:81], v[146:149], v[216:219], v[78:81]
	v_mfma_f32_16x16x32_bf16 v[74:77], v[160:163], v[216:219], v[74:77]
	v_mfma_f32_16x16x32_bf16 v[118:121], v[164:167], v[188:191], v[118:121]
	v_mfma_f32_16x16x32_bf16 v[114:117], v[172:175], v[188:191], v[114:117]
	v_mfma_f32_16x16x32_bf16 v[102:105], v[164:167], v[196:199], v[102:105]
	v_mfma_f32_16x16x32_bf16 v[98:101], v[172:175], v[196:199], v[98:101]
	v_mfma_f32_16x16x32_bf16 v[86:89], v[164:167], v[204:207], v[86:89]
	v_mfma_f32_16x16x32_bf16 v[82:85], v[172:175], v[204:207], v[82:85]
	v_mfma_f32_16x16x32_bf16 v[70:73], v[164:167], v[212:215], v[70:73]
	v_mfma_f32_16x16x32_bf16 v[66:69], v[172:175], v[212:215], v[66:69]
	v_mfma_f32_16x16x32_bf16 v[118:121], v[168:171], v[192:195], v[118:121]
	v_mfma_f32_16x16x32_bf16 v[114:117], v[176:179], v[192:195], v[114:117]
	v_mfma_f32_16x16x32_bf16 v[102:105], v[168:171], v[200:203], v[102:105]
	v_mfma_f32_16x16x32_bf16 v[98:101], v[176:179], v[200:203], v[98:101]
	v_mfma_f32_16x16x32_bf16 v[86:89], v[168:171], v[208:211], v[86:89]
	v_mfma_f32_16x16x32_bf16 v[82:85], v[176:179], v[208:211], v[82:85]
	v_mfma_f32_16x16x32_bf16 v[70:73], v[168:171], v[216:219], v[70:73]
	v_mfma_f32_16x16x32_bf16 v[66:69], v[176:179], v[216:219], v[66:69]
	s_setprio 0
	s_barrier
; #define PG8_STAGE(bufoff, gbase) do { _Pragma("unroll") for (int _i = 0; _i < 2; ++_i) \
;         __builtin_amdgcn_global_load_lds((const unsigned*)((const char*)(gbase) + voff[_i]), (LAS unsigned*)(lds + (bufoff) + ldsw + _i * 8192), 16, 0, 0); } while (0)
; #define PG8_LDA(dst, b, h) do { _Pragma("unroll") for (int m = 0; m < 4; ++m) _Pragma("unroll") for (int k = 0; k < 2; ++k) dst[m][k] = *(const LAS bf16x8*)(lds + PG8_SA(b, h) + aoff + m * 2048 + k * 1024); } while (0)
; #define PG8_MMA(ai, bj, At, Bt) do { __builtin_amdgcn_s_setprio(1); _Pragma("unroll") for (int m = 0; m < 4; ++m) _Pragma("unroll") for (int n = 0; n < 2; ++n) _Pragma("unroll") for (int k = 0; k < 2; ++k) \
;         acc[ai][bj][m][n] = __builtin_amdgcn_mfma_f32_16x16x32_bf16(Bt[n][k], At[m][k], acc[ai][bj][m][n], 0, 0, 0); __builtin_amdgcn_s_setprio(0); } while (0)
; #define PG8_WAIT_V(n) asm volatile("s_waitcnt vmcnt(" #n ")" ::: "memory")
; #define PG8_WAIT_L(n) asm volatile("s_waitcnt lgkmcnt(" #n ")" ::: "memory")
; #define PG8_BAR __builtin_amdgcn_s_barrier()
; #define PG8_SCHED __builtin_amdgcn_sched_barrier(0)
; template <int EPI> ...
;     ...
;             PG8_LDA(At, 1, 1); PG8_STAGE(PG8_SB(1, 0), b3); PG8_STAGE(PG8_SB(1, 1), b3 + hstep); PG8_STAGE(PG8_SA(1, 0), a3);
;             PG8_WAIT_V(8); PG8_WAIT_L(0); PG8_BAR; PG8_MMA(1, 0, At, B0); PG8_MMA(1, 1, At, B1); PG8_BAR; PG8_SCHED;
;         }
;         if (wr == 0) PG8_BAR;
	s_add_i32 s28, s53, s30
	v_lshl_add_u64 v[180:181], v[180:181], 0, s[6:7]
	s_mov_b32 m0, s28
	ds_read_b128 v[188:191], v155 offset:49152
	ds_read_b128 v[192:195], v155 offset:50176
	ds_read_b128 v[196:199], v155 offset:51200
	ds_read_b128 v[200:203], v155 offset:52224
	ds_read_b128 v[204:207], v155 offset:53248
	ds_read_b128 v[208:211], v155 offset:54272
	ds_read_b128 v[212:215], v155 offset:55296
	ds_read_b128 v[216:219], v155 offset:56320
	global_load_lds_dwordx4 v[180:181], off
	s_add_i32 m0, s28, 0x2000
	s_add_u32 s26, s26, 0x20080
	v_lshl_add_u64 v[180:181], v[220:221], 0, s[6:7]
	s_addc_u32 s27, s27, 0
	s_add_i32 s28, s54, s30
	global_load_lds_dwordx4 v[180:181], off
	v_lshl_add_u64 v[180:181], s[26:27], 0, v[130:131]
	s_mov_b32 m0, s28
	s_nop 0
	global_load_lds_dwordx4 v[180:181], off
	v_lshl_add_u64 v[180:181], s[26:27], 0, v[132:133]
	s_add_i32 m0, s28, 0x2000
	s_nop 0
	global_load_lds_dwordx4 v[180:181], off
	v_lshl_add_u64 v[180:181], v[222:223], 0, s[6:7]
	s_mov_b32 m0, s41
	s_nop 0
	global_load_lds_dwordx4 v[180:181], off
	v_lshl_add_u64 v[180:181], v[224:225], 0, s[6:7]
	s_mov_b32 m0, s42
	s_nop 0
	global_load_lds_dwordx4 v[180:181], off
	s_waitcnt vmcnt(8)
	s_waitcnt lgkmcnt(0)
	s_barrier
	s_setprio 1
	s_waitcnt lgkmcnt(0)
	v_mfma_f32_16x16x32_bf16 v[62:65], v[142:145], v[188:191], v[62:65]
	v_mfma_f32_16x16x32_bf16 v[58:61], v[156:159], v[188:191], v[58:61]
	v_mfma_f32_16x16x32_bf16 v[46:49], v[142:145], v[196:199], v[46:49]
	v_mfma_f32_16x16x32_bf16 v[42:45], v[156:159], v[196:199], v[42:45]
	v_mfma_f32_16x16x32_bf16 v[30:33], v[142:145], v[204:207], v[30:33]
	v_mfma_f32_16x16x32_bf16 v[26:29], v[156:159], v[204:207], v[26:29]
	v_mfma_f32_16x16x32_bf16 v[14:17], v[142:145], v[212:215], v[14:17]
	v_mfma_f32_16x16x32_bf16 v[10:13], v[156:159], v[212:215], v[10:13]
	v_mfma_f32_16x16x32_bf16 v[62:65], v[146:149], v[192:195], v[62:65]
	v_mfma_f32_16x16x32_bf16 v[58:61], v[160:163], v[192:195], v[58:61]
	v_mfma_f32_16x16x32_bf16 v[46:49], v[146:149], v[200:203], v[46:49]
	v_mfma_f32_16x16x32_bf16 v[42:45], v[160:163], v[200:203], v[42:45]
	v_mfma_f32_16x16x32_bf16 v[30:33], v[146:149], v[208:211], v[30:33]
	v_mfma_f32_16x16x32_bf16 v[26:29], v[160:163], v[208:211], v[26:29]
	v_mfma_f32_16x16x32_bf16 v[14:17], v[146:149], v[216:219], v[14:17]
	v_mfma_f32_16x16x32_bf16 v[10:13], v[160:163], v[216:219], v[10:13]
	v_mfma_f32_16x16x32_bf16 v[54:57], v[164:167], v[188:191], v[54:57]
	v_mfma_f32_16x16x32_bf16 v[50:53], v[172:175], v[188:191], v[50:53]
	v_mfma_f32_16x16x32_bf16 v[38:41], v[164:167], v[196:199], v[38:41]
	v_mfma_f32_16x16x32_bf16 v[34:37], v[172:175], v[196:199], v[34:37]
	v_mfma_f32_16x16x32_bf16 v[22:25], v[164:167], v[204:207], v[22:25]
	v_mfma_f32_16x16x32_bf16 v[18:21], v[172:175], v[204:207], v[18:21]
	v_mfma_f32_16x16x32_bf16 v[6:9], v[164:167], v[212:215], v[6:9]
	v_mfma_f32_16x16x32_bf16 v[2:5], v[172:175], v[212:215], v[2:5]
	v_mfma_f32_16x16x32_bf16 v[54:57], v[168:171], v[192:195], v[54:57]
	v_mfma_f32_16x16x32_bf16 v[50:53], v[176:179], v[192:195], v[50:53]
	v_mfma_f32_16x16x32_bf16 v[38:41], v[168:171], v[200:203], v[38:41]
	v_mfma_f32_16x16x32_bf16 v[34:37], v[176:179], v[200:203], v[34:37]
	v_mfma_f32_16x16x32_bf16 v[22:25], v[168:171], v[208:211], v[22:25]
	v_mfma_f32_16x16x32_bf16 v[18:21], v[176:179], v[208:211], v[18:21]
	v_mfma_f32_16x16x32_bf16 v[6:9], v[168:171], v[216:219], v[6:9]
	v_mfma_f32_16x16x32_bf16 v[2:5], v[176:179], v[216:219], v[2:5]
	s_setprio 0
	s_barrier
	s_add_i32 s52, s52, 2
	s_add_u32 s24, s24, 0x100
	s_addc_u32 s25, s25, 0
	s_add_u32 s50, s50, 0x100
	s_addc_u32 s51, s51, 0
	s_cmp_gt_u32 s52, 5
	s_cbranch_scc0 .LBB0_737
	s_and_b64 vcc, exec, s[8:9]
	s_cbranch_vccz .LBB0_740
	s_barrier

; #define PG8_STAGE(bufoff, gbase) do { _Pragma("unroll") for (int _i = 0; _i < 2; ++_i) \
;         __builtin_amdgcn_global_load_lds((const unsigned*)((const char*)(gbase) + voff[_i]), (LAS unsigned*)(lds + (bufoff) + ldsw + _i * 8192), 16, 0, 0); } while (0)
; #define PG8_LDA(dst, b, h) do { _Pragma("unroll") for (int m = 0; m < 4; ++m) _Pragma("unroll") for (int k = 0; k < 2; ++k) dst[m][k] = *(const LAS bf16x8*)(lds + PG8_SA(b, h) + aoff + m * 2048 + k * 1024); } while (0)
; #define PG8_LDB(dst, b, h) do { _Pragma("unroll") for (int n = 0; n < 2; ++n) _Pragma("unroll") for (int k = 0; k < 2; ++k) dst[n][k] = *(const LAS bf16x8*)(lds + PG8_SB(b, h) + boff + n * 2048 + k * 1024); } while (0)
; #define PG8_MMA(ai, bj, At, Bt) do { __builtin_amdgcn_s_setprio(1); _Pragma("unroll") for (int m = 0; m < 4; ++m) _Pragma("unroll") for (int n = 0; n < 2; ++n) _Pragma("unroll") for (int k = 0; k < 2; ++k) \
;         acc[ai][bj][m][n] = __builtin_amdgcn_mfma_f32_16x16x32_bf16(Bt[n][k], At[m][k], acc[ai][bj][m][n], 0, 0, 0); __builtin_amdgcn_s_setprio(0); } while (0)
; #define PG8_WAIT_V(n) asm volatile("s_waitcnt vmcnt(" #n ")" ::: "memory")
; #define PG8_WAIT_L(n) asm volatile("s_waitcnt lgkmcnt(" #n ")" ::: "memory")
; #define PG8_BAR __builtin_amdgcn_s_barrier()
; #define PG8_SCHED __builtin_amdgcn_sched_barrier(0)
; template <int EPI> ...
;     ...
;         for (int t = 0; t < cnk; t += 2) {
;             const bool last = (t == cnk - 2);
;             const char* a1 = cA + (size_t)(t + 1) * kstep;
;             const char* a2 = last ? nA : cA + (size_t)(t + 2) * kstep; const char* b2 = last ? nB : cB + (size_t)(t + 2) * kstep;
;             const char* a3 = a2 + kstep; const char* b3 = b2 + kstep;
;             PG8_LDB(B0, 0, 0); PG8_LDB(B1, 0, 1); PG8_SCHED; PG8_LDA(At, 0, 0); PG8_STAGE(PG8_SA(1, 1), a1 + hstep);
;             PG8_WAIT_V(8); PG8_WAIT_L(0); PG8_BAR; PG8_MMA(0, 0, At, B0); PG8_MMA(0, 1, At, B1); PG8_BAR; PG8_SCHED;
;             PG8_LDA(At, 0, 1); PG8_STAGE(PG8_SB(0, 0), b2); PG8_STAGE(PG8_SB(0, 1), b2 + hstep); PG8_STAGE(PG8_SA(0, 0), a2);
;             PG8_WAIT_V(8); PG8_WAIT_L(0); PG8_BAR; PG8_MMA(1, 0, At, B0); PG8_MMA(1, 1, At, B1); PG8_BAR; PG8_SCHED;
.LBB0_825:
	ds_read_b128 v[142:145], v152
	ds_read_b128 v[156:159], v152 offset:1024
	ds_read_b128 v[160:163], v152 offset:2048
	ds_read_b128 v[164:167], v152 offset:3072
	ds_read_b128 v[168:171], v153
	ds_read_b128 v[172:175], v153 offset:1024
	ds_read_b128 v[176:179], v153 offset:2048
	ds_read_b128 v[188:191], v153 offset:3072
	s_add_i32 s57, s34, 2
	s_add_u32 s35, s30, 0xfffc0080
	s_addc_u32 s36, s31, -1
	s_cmp_eq_u32 s54, s34
	s_cselect_b32 s34, s53, s55
	s_cselect_b32 s37, s5, s36
	s_cselect_b32 s36, s19, s35
	s_cselect_b32 s35, s17, s56
	v_lshl_add_u64 v[146:147], s[30:31], 0, v[136:137]
	s_add_i32 m0, s7, 0xc000
	ds_read_b128 v[192:195], v154
	ds_read_b128 v[196:199], v154 offset:1024
	ds_read_b128 v[200:203], v154 offset:2048
	ds_read_b128 v[204:207], v154 offset:3072
	ds_read_b128 v[208:211], v154 offset:4096
	ds_read_b128 v[212:215], v154 offset:5120
	ds_read_b128 v[216:219], v154 offset:6144
	ds_read_b128 v[220:223], v154 offset:7168
	global_load_lds_dwordx4 v[146:147], off
	v_lshl_add_u64 v[146:147], s[30:31], 0, v[138:139]
	s_add_i32 m0, s7, 0xe000
	s_nop 0
	global_load_lds_dwordx4 v[146:147], off
	s_waitcnt vmcnt(8)
	s_waitcnt lgkmcnt(0)
	s_barrier
	s_setprio 1
	s_waitcnt lgkmcnt(0)
	v_mfma_f32_16x16x32_bf16 v[126:129], v[142:145], v[192:195], v[126:129]
	v_mfma_f32_16x16x32_bf16 v[122:125], v[160:163], v[192:195], v[122:125]
	v_mfma_f32_16x16x32_bf16 v[118:121], v[142:145], v[200:203], v[118:121]
	v_mfma_f32_16x16x32_bf16 v[114:117], v[160:163], v[200:203], v[114:117]
	v_mfma_f32_16x16x32_bf16 v[106:109], v[142:145], v[208:211], v[106:109]
	v_mfma_f32_16x16x32_bf16 v[98:101], v[160:163], v[208:211], v[98:101]
	v_mfma_f32_16x16x32_bf16 v[90:93], v[142:145], v[216:219], v[90:93]
	v_mfma_f32_16x16x32_bf16 v[82:85], v[160:163], v[216:219], v[82:85]
	v_mfma_f32_16x16x32_bf16 v[126:129], v[156:159], v[196:199], v[126:129]
	v_mfma_f32_16x16x32_bf16 v[122:125], v[164:167], v[196:199], v[122:125]
	v_mfma_f32_16x16x32_bf16 v[118:121], v[156:159], v[204:207], v[118:121]
	v_mfma_f32_16x16x32_bf16 v[114:117], v[164:167], v[204:207], v[114:117]
	v_mfma_f32_16x16x32_bf16 v[106:109], v[156:159], v[212:215], v[106:109]
	v_mfma_f32_16x16x32_bf16 v[98:101], v[164:167], v[212:215], v[98:101]
	v_mfma_f32_16x16x32_bf16 v[90:93], v[156:159], v[220:223], v[90:93]
	v_mfma_f32_16x16x32_bf16 v[82:85], v[164:167], v[220:223], v[82:85]
	v_mfma_f32_16x16x32_bf16 v[110:113], v[168:171], v[192:195], v[110:113]
	v_mfma_f32_16x16x32_bf16 v[102:105], v[176:179], v[192:195], v[102:105]
	v_mfma_f32_16x16x32_bf16 v[94:97], v[168:171], v[200:203], v[94:97]
	v_mfma_f32_16x16x32_bf16 v[86:89], v[176:179], v[200:203], v[86:89]
	v_mfma_f32_16x16x32_bf16 v[78:81], v[168:171], v[208:211], v[78:81]
	v_mfma_f32_16x16x32_bf16 v[74:77], v[176:179], v[208:211], v[74:77]
	v_mfma_f32_16x16x32_bf16 v[70:73], v[168:171], v[216:219], v[70:73]
	v_mfma_f32_16x16x32_bf16 v[66:69], v[176:179], v[216:219], v[66:69]
	v_mfma_f32_16x16x32_bf16 v[110:113], v[172:175], v[196:199], v[110:113]
	v_mfma_f32_16x16x32_bf16 v[102:105], v[188:191], v[196:199], v[102:105]
	v_mfma_f32_16x16x32_bf16 v[94:97], v[172:175], v[204:207], v[94:97]
	v_mfma_f32_16x16x32_bf16 v[86:89], v[188:191], v[204:207], v[86:89]
	v_mfma_f32_16x16x32_bf16 v[78:81], v[172:175], v[212:215], v[78:81]
	v_mfma_f32_16x16x32_bf16 v[74:77], v[188:191], v[212:215], v[74:77]
	v_mfma_f32_16x16x32_bf16 v[70:73], v[172:175], v[220:223], v[70:73]
	v_mfma_f32_16x16x32_bf16 v[66:69], v[188:191], v[220:223], v[66:69]
	s_setprio 0
	s_barrier
	s_add_i32 s58, s46, s39
	v_lshl_add_u64 v[146:147], s[34:35], 0, v[130:131]
	s_mov_b32 m0, s58
	ds_read_b128 v[192:195], v154 offset:16384
	ds_read_b128 v[196:199], v154 offset:17408
	ds_read_b128 v[200:203], v154 offset:18432
	ds_read_b128 v[204:207], v154 offset:19456
	ds_read_b128 v[208:211], v154 offset:20480
	ds_read_b128 v[212:215], v154 offset:21504
	ds_read_b128 v[216:219], v154 offset:22528
	ds_read_b128 v[220:223], v154 offset:23552
	global_load_lds_dwordx4 v[146:147], off
	s_add_i32 m0, s58, 0x2000
	s_add_u32 s58, s34, 0x40000
	v_lshl_add_u64 v[180:181], s[34:35], 0, v[132:133]
	s_addc_u32 s59, s35, 0
	s_add_i32 s60, s47, s39
	global_load_lds_dwordx4 v[180:181], off
	v_lshl_add_u64 v[224:225], s[58:59], 0, v[130:131]
	s_mov_b32 m0, s60
	v_lshl_add_u64 v[226:227], s[36:37], 0, v[132:133]
	global_load_lds_dwordx4 v[224:225], off
	v_lshl_add_u64 v[224:225], s[58:59], 0, v[132:133]
	s_add_i32 m0, s60, 0x2000
	s_nop 0
	global_load_lds_dwordx4 v[224:225], off
	v_lshl_add_u64 v[224:225], s[36:37], 0, v[130:131]
	s_mov_b32 m0, s7
	s_nop 0
	global_load_lds_dwordx4 v[224:225], off
	s_mov_b32 m0, s40
	s_nop 0
	global_load_lds_dwordx4 v[226:227], off
	s_waitcnt vmcnt(8)
	s_waitcnt lgkmcnt(0)
	s_barrier
; #define PG8_STAGE(bufoff, gbase) do { _Pragma("unroll") for (int _i = 0; _i < 2; ++_i) \
;         __builtin_amdgcn_global_load_lds((const unsigned*)((const char*)(gbase) + voff[_i]), (LAS unsigned*)(lds + (bufoff) + ldsw + _i * 8192), 16, 0, 0); } while (0)
; #define PG8_LDA(dst, b, h) do { _Pragma("unroll") for (int m = 0; m < 4; ++m) _Pragma("unroll") for (int k = 0; k < 2; ++k) dst[m][k] = *(const LAS bf16x8*)(lds + PG8_SA(b, h) + aoff + m * 2048 + k * 1024); } while (0)
; #define PG8_LDB(dst, b, h) do { _Pragma("unroll") for (int n = 0; n < 2; ++n) _Pragma("unroll") for (int k = 0; k < 2; ++k) dst[n][k] = *(const LAS bf16x8*)(lds + PG8_SB(b, h) + boff + n * 2048 + k * 1024); } while (0)
; #define PG8_MMA(ai, bj, At, Bt) do { __builtin_amdgcn_s_setprio(1); _Pragma("unroll") for (int m = 0; m < 4; ++m) _Pragma("unroll") for (int n = 0; n < 2; ++n) _Pragma("unroll") for (int k = 0; k < 2; ++k) \
;         acc[ai][bj][m][n] = __builtin_amdgcn_mfma_f32_16x16x32_bf16(Bt[n][k], At[m][k], acc[ai][bj][m][n], 0, 0, 0); __builtin_amdgcn_s_setprio(0); } while (0)
; #define PG8_WAIT_V(n) asm volatile("s_waitcnt vmcnt(" #n ")" ::: "memory")
; #define PG8_WAIT_L(n) asm volatile("s_waitcnt lgkmcnt(" #n ")" ::: "memory")
; #define PG8_BAR __builtin_amdgcn_s_barrier()
; #define PG8_SCHED __builtin_amdgcn_sched_barrier(0)
; template <int EPI> ...
;     ...
;             PG8_WAIT_V(8); PG8_WAIT_L(0); PG8_BAR; PG8_MMA(1, 0, At, B0); PG8_MMA(1, 1, At, B1); PG8_BAR; PG8_SCHED;
;             PG8_LDB(B0, 1, 0); PG8_LDB(B1, 1, 1); PG8_SCHED; PG8_LDA(At, 1, 0); PG8_STAGE(PG8_SA(0, 1), a2 + hstep);
;             PG8_WAIT_V(8); PG8_WAIT_L(0); PG8_BAR; PG8_MMA(0, 0, At, B0); PG8_MMA(0, 1, At, B1); PG8_BAR; PG8_SCHED;
	s_setprio 1
	s_waitcnt lgkmcnt(0)
	v_mfma_f32_16x16x32_bf16 v[62:65], v[142:145], v[192:195], v[62:65]
	v_mfma_f32_16x16x32_bf16 v[58:61], v[160:163], v[192:195], v[58:61]
	v_mfma_f32_16x16x32_bf16 v[54:57], v[142:145], v[200:203], v[54:57]
	v_mfma_f32_16x16x32_bf16 v[50:53], v[160:163], v[200:203], v[50:53]
	v_mfma_f32_16x16x32_bf16 v[42:45], v[142:145], v[208:211], v[42:45]
	v_mfma_f32_16x16x32_bf16 v[34:37], v[160:163], v[208:211], v[34:37]
	v_mfma_f32_16x16x32_bf16 v[26:29], v[142:145], v[216:219], v[26:29]
	v_mfma_f32_16x16x32_bf16 v[18:21], v[160:163], v[216:219], v[18:21]
	v_mfma_f32_16x16x32_bf16 v[62:65], v[156:159], v[196:199], v[62:65]
	v_mfma_f32_16x16x32_bf16 v[58:61], v[164:167], v[196:199], v[58:61]
	v_mfma_f32_16x16x32_bf16 v[54:57], v[156:159], v[204:207], v[54:57]
	v_mfma_f32_16x16x32_bf16 v[50:53], v[164:167], v[204:207], v[50:53]
	v_mfma_f32_16x16x32_bf16 v[42:45], v[156:159], v[212:215], v[42:45]
	v_mfma_f32_16x16x32_bf16 v[34:37], v[164:167], v[212:215], v[34:37]
	v_mfma_f32_16x16x32_bf16 v[26:29], v[156:159], v[220:223], v[26:29]
	v_mfma_f32_16x16x32_bf16 v[18:21], v[164:167], v[220:223], v[18:21]
	v_mfma_f32_16x16x32_bf16 v[46:49], v[168:171], v[192:195], v[46:49]
	v_mfma_f32_16x16x32_bf16 v[38:41], v[176:179], v[192:195], v[38:41]
	v_mfma_f32_16x16x32_bf16 v[30:33], v[168:171], v[200:203], v[30:33]
	v_mfma_f32_16x16x32_bf16 v[22:25], v[176:179], v[200:203], v[22:25]
	v_mfma_f32_16x16x32_bf16 v[14:17], v[168:171], v[208:211], v[14:17]
	v_mfma_f32_16x16x32_bf16 v[10:13], v[176:179], v[208:211], v[10:13]
	v_mfma_f32_16x16x32_bf16 v[6:9], v[168:171], v[216:219], v[6:9]
	v_mfma_f32_16x16x32_bf16 v[2:5], v[176:179], v[216:219], v[2:5]
	v_mfma_f32_16x16x32_bf16 v[46:49], v[172:175], v[196:199], v[46:49]
	v_mfma_f32_16x16x32_bf16 v[38:41], v[188:191], v[196:199], v[38:41]
	v_mfma_f32_16x16x32_bf16 v[30:33], v[172:175], v[204:207], v[30:33]
	v_mfma_f32_16x16x32_bf16 v[22:25], v[188:191], v[204:207], v[22:25]
	v_mfma_f32_16x16x32_bf16 v[14:17], v[172:175], v[212:215], v[14:17]
	v_mfma_f32_16x16x32_bf16 v[10:13], v[188:191], v[212:215], v[10:13]
	v_mfma_f32_16x16x32_bf16 v[6:9], v[172:175], v[220:223], v[6:9]
	v_mfma_f32_16x16x32_bf16 v[2:5], v[188:191], v[220:223], v[2:5]
	s_setprio 0
	s_barrier
	s_add_i32 s58, 0, 0x18000
	v_add_u32_e32 v155, s58, v149
	s_add_i32 s59, 0, 0x1c000
	ds_read_b128 v[142:145], v155
	ds_read_b128 v[156:159], v155 offset:1024
	ds_read_b128 v[160:163], v155 offset:2048
	ds_read_b128 v[164:167], v155 offset:3072
	v_add_u32_e32 v155, s59, v149
	ds_read_b128 v[168:171], v155
	ds_read_b128 v[172:175], v155 offset:1024
	ds_read_b128 v[176:179], v155 offset:2048
	ds_read_b128 v[188:191], v155 offset:3072
	s_add_u32 s36, s36, 0x40000
	s_addc_u32 s37, s37, 0
	s_mov_b32 m0, s41
	v_lshl_add_u64 v[228:229], s[36:37], 0, v[130:131]
	ds_read_b128 v[192:195], v154 offset:32768
	ds_read_b128 v[196:199], v154 offset:33792
	ds_read_b128 v[200:203], v154 offset:34816
	ds_read_b128 v[204:207], v154 offset:35840
	ds_read_b128 v[208:211], v154 offset:36864
	ds_read_b128 v[212:215], v154 offset:37888
	ds_read_b128 v[216:219], v154 offset:38912
	ds_read_b128 v[220:223], v154 offset:39936
	global_load_lds_dwordx4 v[228:229], off
	v_lshl_add_u64 v[228:229], s[36:37], 0, v[132:133]
	s_mov_b32 m0, s42
	s_nop 0
	global_load_lds_dwordx4 v[228:229], off
	s_waitcnt vmcnt(8)
	s_waitcnt lgkmcnt(0)
	s_barrier
	s_setprio 1
	s_waitcnt lgkmcnt(0)
	v_mfma_f32_16x16x32_bf16 v[126:129], v[142:145], v[192:195], v[126:129]
	v_mfma_f32_16x16x32_bf16 v[122:125], v[160:163], v[192:195], v[122:125]
	v_mfma_f32_16x16x32_bf16 v[118:121], v[142:145], v[200:203], v[118:121]
	v_mfma_f32_16x16x32_bf16 v[114:117], v[160:163], v[200:203], v[114:117]
	v_mfma_f32_16x16x32_bf16 v[106:109], v[142:145], v[208:211], v[106:109]
	v_mfma_f32_16x16x32_bf16 v[98:101], v[160:163], v[208:211], v[98:101]
	v_mfma_f32_16x16x32_bf16 v[90:93], v[142:145], v[216:219], v[90:93]
	v_mfma_f32_16x16x32_bf16 v[82:85], v[160:163], v[216:219], v[82:85]
	v_mfma_f32_16x16x32_bf16 v[126:129], v[156:159], v[196:199], v[126:129]
	v_mfma_f32_16x16x32_bf16 v[122:125], v[164:167], v[196:199], v[122:125]
	v_mfma_f32_16x16x32_bf16 v[118:121], v[156:159], v[204:207], v[118:121]
	v_mfma_f32_16x16x32_bf16 v[114:117], v[164:167], v[204:207], v[114:117]
	v_mfma_f32_16x16x32_bf16 v[106:109], v[156:159], v[212:215], v[106:109]
	v_mfma_f32_16x16x32_bf16 v[98:101], v[164:167], v[212:215], v[98:101]
	v_mfma_f32_16x16x32_bf16 v[90:93], v[156:159], v[220:223], v[90:93]
	v_mfma_f32_16x16x32_bf16 v[82:85], v[164:167], v[220:223], v[82:85]
	v_mfma_f32_16x16x32_bf16 v[110:113], v[168:171], v[192:195], v[110:113]
	v_mfma_f32_16x16x32_bf16 v[102:105], v[176:179], v[192:195], v[102:105]
	v_mfma_f32_16x16x32_bf16 v[94:97], v[168:171], v[200:203], v[94:97]
	v_mfma_f32_16x16x32_bf16 v[86:89], v[176:179], v[200:203], v[86:89]
	v_mfma_f32_16x16x32_bf16 v[78:81], v[168:171], v[208:211], v[78:81]
	v_mfma_f32_16x16x32_bf16 v[74:77], v[176:179], v[208:211], v[74:77]
	v_mfma_f32_16x16x32_bf16 v[70:73], v[168:171], v[216:219], v[70:73]
	v_mfma_f32_16x16x32_bf16 v[66:69], v[176:179], v[216:219], v[66:69]
	v_mfma_f32_16x16x32_bf16 v[110:113], v[172:175], v[196:199], v[110:113]
	v_mfma_f32_16x16x32_bf16 v[102:105], v[188:191], v[196:199], v[102:105]
	v_mfma_f32_16x16x32_bf16 v[94:97], v[172:175], v[204:207], v[94:97]
	v_mfma_f32_16x16x32_bf16 v[86:89], v[188:191], v[204:207], v[86:89]
	v_mfma_f32_16x16x32_bf16 v[78:81], v[172:175], v[212:215], v[78:81]
	v_mfma_f32_16x16x32_bf16 v[74:77], v[188:191], v[212:215], v[74:77]
	v_mfma_f32_16x16x32_bf16 v[70:73], v[172:175], v[220:223], v[70:73]
	v_mfma_f32_16x16x32_bf16 v[66:69], v[188:191], v[220:223], v[66:69]
	s_setprio 0
	s_barrier
; #define PG8_STAGE(bufoff, gbase) do { _Pragma("unroll") for (int _i = 0; _i < 2; ++_i) \
;         __builtin_amdgcn_global_load_lds((const unsigned*)((const char*)(gbase) + voff[_i]), (LAS unsigned*)(lds + (bufoff) + ldsw + _i * 8192), 16, 0, 0); } while (0)
; #define PG8_LDA(dst, b, h) do { _Pragma("unroll") for (int m = 0; m < 4; ++m) _Pragma("unroll") for (int k = 0; k < 2; ++k) dst[m][k] = *(const LAS bf16x8*)(lds + PG8_SA(b, h) + aoff + m * 2048 + k * 1024); } while (0)
; #define PG8_MMA(ai, bj, At, Bt) do { __builtin_amdgcn_s_setprio(1); _Pragma("unroll") for (int m = 0; m < 4; ++m) _Pragma("unroll") for (int n = 0; n < 2; ++n) _Pragma("unroll") for (int k = 0; k < 2; ++k) \
;         acc[ai][bj][m][n] = __builtin_amdgcn_mfma_f32_16x16x32_bf16(Bt[n][k], At[m][k], acc[ai][bj][m][n], 0, 0, 0); __builtin_amdgcn_s_setprio(0); } while (0)
; #define PG8_WAIT_V(n) asm volatile("s_waitcnt vmcnt(" #n ")" ::: "memory")
; #define PG8_WAIT_L(n) asm volatile("s_waitcnt lgkmcnt(" #n ")" ::: "memory")
; #define PG8_BAR __builtin_amdgcn_s_barrier()
; #define PG8_SCHED __builtin_amdgcn_sched_barrier(0)
; template <int EPI> ...
;     ...
;             PG8_LDA(At, 1, 1); PG8_STAGE(PG8_SB(1, 0), b3); PG8_STAGE(PG8_SB(1, 1), b3 + hstep); PG8_STAGE(PG8_SA(1, 0), a3);
;             PG8_WAIT_V(8); PG8_WAIT_L(0); PG8_BAR; PG8_MMA(1, 0, At, B0); PG8_MMA(1, 1, At, B1); PG8_BAR; PG8_SCHED;
;         }
;         if (wr == 0) PG8_BAR;
;         if (SPLIT && cur_slice >= 0) {
	s_add_i32 s36, s58, s39
	v_lshl_add_u64 v[146:147], v[146:147], 0, s[10:11]
	s_mov_b32 m0, s36
	ds_read_b128 v[192:195], v154 offset:49152
	ds_read_b128 v[196:199], v154 offset:50176
	ds_read_b128 v[200:203], v154 offset:51200
	ds_read_b128 v[204:207], v154 offset:52224
	ds_read_b128 v[208:211], v154 offset:53248
	ds_read_b128 v[212:215], v154 offset:54272
	ds_read_b128 v[216:219], v154 offset:55296
	ds_read_b128 v[220:223], v154 offset:56320
	global_load_lds_dwordx4 v[146:147], off
	s_add_i32 m0, s36, 0x2000
	s_add_u32 s34, s34, 0x40080
	v_lshl_add_u64 v[146:147], v[180:181], 0, s[10:11]
	s_addc_u32 s35, s35, 0
	s_add_i32 s36, s59, s39
	global_load_lds_dwordx4 v[146:147], off
	v_lshl_add_u64 v[146:147], s[34:35], 0, v[130:131]
	s_mov_b32 m0, s36
	s_nop 0
	global_load_lds_dwordx4 v[146:147], off
	v_lshl_add_u64 v[146:147], s[34:35], 0, v[132:133]
	s_add_i32 m0, s36, 0x2000
	s_nop 0
	global_load_lds_dwordx4 v[146:147], off
	v_lshl_add_u64 v[146:147], v[224:225], 0, s[10:11]
	s_mov_b32 m0, s43
	s_nop 0
	global_load_lds_dwordx4 v[146:147], off
	v_lshl_add_u64 v[146:147], v[226:227], 0, s[10:11]
	s_mov_b32 m0, s44
	s_nop 0
	global_load_lds_dwordx4 v[146:147], off
	s_waitcnt vmcnt(8)
	s_waitcnt lgkmcnt(0)
	s_barrier
	s_setprio 1
	s_waitcnt lgkmcnt(0)
	v_mfma_f32_16x16x32_bf16 v[62:65], v[142:145], v[192:195], v[62:65]
	v_mfma_f32_16x16x32_bf16 v[58:61], v[160:163], v[192:195], v[58:61]
	v_mfma_f32_16x16x32_bf16 v[54:57], v[142:145], v[200:203], v[54:57]
	v_mfma_f32_16x16x32_bf16 v[50:53], v[160:163], v[200:203], v[50:53]
	v_mfma_f32_16x16x32_bf16 v[42:45], v[142:145], v[208:211], v[42:45]
	v_mfma_f32_16x16x32_bf16 v[34:37], v[160:163], v[208:211], v[34:37]
	v_mfma_f32_16x16x32_bf16 v[26:29], v[142:145], v[216:219], v[26:29]
	v_mfma_f32_16x16x32_bf16 v[18:21], v[160:163], v[216:219], v[18:21]
	v_mfma_f32_16x16x32_bf16 v[62:65], v[156:159], v[196:199], v[62:65]
	v_mfma_f32_16x16x32_bf16 v[58:61], v[164:167], v[196:199], v[58:61]
	v_mfma_f32_16x16x32_bf16 v[54:57], v[156:159], v[204:207], v[54:57]
	v_mfma_f32_16x16x32_bf16 v[50:53], v[164:167], v[204:207], v[50:53]
	v_mfma_f32_16x16x32_bf16 v[42:45], v[156:159], v[212:215], v[42:45]
	v_mfma_f32_16x16x32_bf16 v[34:37], v[164:167], v[212:215], v[34:37]
	v_mfma_f32_16x16x32_bf16 v[26:29], v[156:159], v[220:223], v[26:29]
	v_mfma_f32_16x16x32_bf16 v[18:21], v[164:167], v[220:223], v[18:21]
	v_mfma_f32_16x16x32_bf16 v[46:49], v[168:171], v[192:195], v[46:49]
	v_mfma_f32_16x16x32_bf16 v[38:41], v[176:179], v[192:195], v[38:41]
	v_mfma_f32_16x16x32_bf16 v[30:33], v[168:171], v[200:203], v[30:33]
	v_mfma_f32_16x16x32_bf16 v[22:25], v[176:179], v[200:203], v[22:25]
	v_mfma_f32_16x16x32_bf16 v[14:17], v[168:171], v[208:211], v[14:17]
	v_mfma_f32_16x16x32_bf16 v[10:13], v[176:179], v[208:211], v[10:13]
	v_mfma_f32_16x16x32_bf16 v[6:9], v[168:171], v[216:219], v[6:9]
	v_mfma_f32_16x16x32_bf16 v[2:5], v[176:179], v[216:219], v[2:5]
	v_mfma_f32_16x16x32_bf16 v[46:49], v[172:175], v[196:199], v[46:49]
	v_mfma_f32_16x16x32_bf16 v[38:41], v[188:191], v[196:199], v[38:41]
	v_mfma_f32_16x16x32_bf16 v[30:33], v[172:175], v[204:207], v[30:33]
	v_mfma_f32_16x16x32_bf16 v[22:25], v[188:191], v[204:207], v[22:25]
	v_mfma_f32_16x16x32_bf16 v[14:17], v[172:175], v[212:215], v[14:17]
	v_mfma_f32_16x16x32_bf16 v[10:13], v[188:191], v[212:215], v[10:13]
	v_mfma_f32_16x16x32_bf16 v[6:9], v[172:175], v[220:223], v[6:9]
	v_mfma_f32_16x16x32_bf16 v[2:5], v[188:191], v[220:223], v[2:5]
	s_setprio 0
	s_barrier
	s_add_u32 s30, s30, 0x100
	s_addc_u32 s31, s31, 0
	s_add_u32 s55, s55, 0x100
	s_addc_u32 s56, s56, 0
	s_cmp_ge_u32 s57, s52
	s_mov_b32 s34, s57
	s_cbranch_scc0 .LBB0_825
	s_and_b64 vcc, exec, s[12:13]
	s_cbranch_vccz .LBB0_830
	s_barrier
	s_cmp_lt_i32 s0, 0
	s_mov_b64 s[30:31], -1
	s_cbranch_scc1 .LBB0_831

; #define PG8_STAGE(bufoff, gbase) do { _Pragma("unroll") for (int _i = 0; _i < 2; ++_i) \
;         __builtin_amdgcn_global_load_lds((const unsigned*)((const char*)(gbase) + voff[_i]), (LAS unsigned*)(lds + (bufoff) + ldsw + _i * 8192), 16, 0, 0); } while (0)
; #define PG8_LDA(dst, b, h) do { _Pragma("unroll") for (int m = 0; m < 4; ++m) _Pragma("unroll") for (int k = 0; k < 2; ++k) dst[m][k] = *(const LAS bf16x8*)(lds + PG8_SA(b, h) + aoff + m * 2048 + k * 1024); } while (0)
; #define PG8_MMA(ai, bj, At, Bt) do { __builtin_amdgcn_s_setprio(1); _Pragma("unroll") for (int m = 0; m < 4; ++m) _Pragma("unroll") for (int n = 0; n < 2; ++n) _Pragma("unroll") for (int k = 0; k < 2; ++k) \
;         acc[ai][bj][m][n] = __builtin_amdgcn_mfma_f32_16x16x32_bf16(Bt[n][k], At[m][k], acc[ai][bj][m][n], 0, 0, 0); __builtin_amdgcn_s_setprio(0); } while (0)
; #define PG8_WAIT_V(n) asm volatile("s_waitcnt vmcnt(" #n ")" ::: "memory")
; #define PG8_WAIT_L(n) asm volatile("s_waitcnt lgkmcnt(" #n ")" ::: "memory")
; #define PG8_BAR __builtin_amdgcn_s_barrier()
; #define PG8_SCHED __builtin_amdgcn_sched_barrier(0)
; template <int EPI> ...
;     ...
;             PG8_WAIT_V(8); PG8_WAIT_L(0); PG8_BAR; PG8_MMA(0, 0, At, B0); PG8_MMA(0, 1, At, B1); PG8_BAR; PG8_SCHED;
;             PG8_LDA(At, 0, 1); PG8_STAGE(PG8_SB(0, 0), b2); PG8_STAGE(PG8_SB(0, 1), b2 + hstep); PG8_STAGE(PG8_SA(0, 0), a2);
;             PG8_WAIT_V(8); PG8_WAIT_L(0); PG8_BAR; PG8_MMA(1, 0, At, B0); PG8_MMA(1, 1, At, B1); PG8_BAR; PG8_SCHED;
.Lup_wdone_0:
	s_waitcnt lgkmcnt(0)
	s_barrier
	s_setprio 1
	s_waitcnt lgkmcnt(0)
	v_mfma_f32_16x16x32_bf16 v[150:153], v[38:41], v[162:165], v[150:153]
	v_mfma_f32_16x16x32_bf16 v[158:161], v[46:49], v[162:165], v[158:161]
	v_mfma_f32_16x16x32_bf16 v[134:137], v[38:41], v[170:173], v[134:137]
	v_mfma_f32_16x16x32_bf16 v[142:145], v[46:49], v[170:173], v[142:145]
	v_mfma_f32_16x16x32_bf16 v[118:121], v[38:41], v[178:181], v[118:121]
	v_mfma_f32_16x16x32_bf16 v[126:129], v[46:49], v[178:181], v[126:129]
	v_mfma_f32_16x16x32_bf16 v[110:113], v[38:41], v[218:221], v[110:113]
	v_mfma_f32_16x16x32_bf16 v[106:109], v[46:49], v[218:221], v[106:109]
	v_mfma_f32_16x16x32_bf16 v[150:153], v[42:45], v[166:169], v[150:153]
	v_mfma_f32_16x16x32_bf16 v[158:161], v[50:53], v[166:169], v[158:161]
	v_mfma_f32_16x16x32_bf16 v[134:137], v[42:45], v[174:177], v[134:137]
	v_mfma_f32_16x16x32_bf16 v[142:145], v[50:53], v[174:177], v[142:145]
	v_mfma_f32_16x16x32_bf16 v[118:121], v[42:45], v[214:217], v[118:121]
	v_mfma_f32_16x16x32_bf16 v[126:129], v[50:53], v[214:217], v[126:129]
	v_mfma_f32_16x16x32_bf16 v[110:113], v[42:45], v[222:225], v[110:113]
	v_mfma_f32_16x16x32_bf16 v[106:109], v[50:53], v[222:225], v[106:109]
	v_mfma_f32_16x16x32_bf16 v[146:149], v[54:57], v[162:165], v[146:149]
	v_mfma_f32_16x16x32_bf16 v[154:157], v[66:69], v[162:165], v[154:157]
	v_mfma_f32_16x16x32_bf16 v[130:133], v[54:57], v[170:173], v[130:133]
	v_mfma_f32_16x16x32_bf16 v[138:141], v[66:69], v[170:173], v[138:141]
	v_mfma_f32_16x16x32_bf16 v[114:117], v[54:57], v[178:181], v[114:117]
	v_mfma_f32_16x16x32_bf16 v[122:125], v[66:69], v[178:181], v[122:125]
	v_mfma_f32_16x16x32_bf16 v[102:105], v[54:57], v[218:221], v[102:105]
	v_mfma_f32_16x16x32_bf16 v[98:101], v[66:69], v[218:221], v[98:101]
	v_mfma_f32_16x16x32_bf16 v[146:149], v[58:61], v[166:169], v[146:149]
	v_mfma_f32_16x16x32_bf16 v[154:157], v[70:73], v[166:169], v[154:157]
	v_mfma_f32_16x16x32_bf16 v[130:133], v[58:61], v[174:177], v[130:133]
	v_mfma_f32_16x16x32_bf16 v[138:141], v[70:73], v[174:177], v[138:141]
	v_mfma_f32_16x16x32_bf16 v[114:117], v[58:61], v[214:217], v[114:117]
	v_mfma_f32_16x16x32_bf16 v[122:125], v[70:73], v[214:217], v[122:125]
	v_mfma_f32_16x16x32_bf16 v[102:105], v[58:61], v[222:225], v[102:105]
	v_mfma_f32_16x16x32_bf16 v[98:101], v[70:73], v[222:225], v[98:101]
	s_setprio 0
	s_barrier
	s_add_i32 s84, s75, s65
	v_lshl_add_u64 v[230:231], s[58:59], 0, v[194:195]
	s_mov_b32 m0, s84
	ds_read_b128 v[162:165], v193 offset:16384
	ds_read_b128 v[166:169], v193 offset:17408
	ds_read_b128 v[170:173], v193 offset:18432
	ds_read_b128 v[174:177], v193 offset:19456
	ds_read_b128 v[178:181], v193 offset:20480
	ds_read_b128 v[214:217], v193 offset:21504
	ds_read_b128 v[218:221], v193 offset:22528
	ds_read_b128 v[222:225], v193 offset:23552
	global_load_lds_dwordx4 v[230:231], off
	s_add_i32 m0, s84, 0x2000
	s_add_u32 s84, s58, 0x40000
	v_lshl_add_u64 v[232:233], s[58:59], 0, v[196:197]
	s_addc_u32 s85, s59, 0
	s_add_i32 s86, s76, s65
	global_load_lds_dwordx4 v[232:233], off
	v_lshl_add_u64 v[226:227], s[84:85], 0, v[194:195]
	s_mov_b32 m0, s86
	v_lshl_add_u64 v[234:235], s[60:61], 0, v[194:195]
	global_load_lds_dwordx4 v[226:227], off
	v_lshl_add_u64 v[226:227], s[84:85], 0, v[196:197]
	s_add_i32 m0, s86, 0x2000
	v_lshl_add_u64 v[236:237], s[60:61], 0, v[196:197]
	global_load_lds_dwordx4 v[226:227], off
	s_mov_b32 m0, s66
	s_nop 0
	global_load_lds_dwordx4 v[234:235], off
	s_mov_b32 m0, s67
	s_nop 0
	global_load_lds_dwordx4 v[236:237], off
	s_cmp_lg_u32 s83, -2
	s_cbranch_scc1 .Lup_strict_1
	s_cmp_lt_u32 s70, 2
	s_cbranch_scc1 .Lup_strict_1
	s_waitcnt vmcnt(24)
	s_branch .Lup_wdone_1

; #define PG8_STAGE(bufoff, gbase) do { _Pragma("unroll") for (int _i = 0; _i < 2; ++_i) \
;         __builtin_amdgcn_global_load_lds((const unsigned*)((const char*)(gbase) + voff[_i]), (LAS unsigned*)(lds + (bufoff) + ldsw + _i * 8192), 16, 0, 0); } while (0)
; #define PG8_LDA(dst, b, h) do { _Pragma("unroll") for (int m = 0; m < 4; ++m) _Pragma("unroll") for (int k = 0; k < 2; ++k) dst[m][k] = *(const LAS bf16x8*)(lds + PG8_SA(b, h) + aoff + m * 2048 + k * 1024); } while (0)
; #define PG8_LDB(dst, b, h) do { _Pragma("unroll") for (int n = 0; n < 2; ++n) _Pragma("unroll") for (int k = 0; k < 2; ++k) dst[n][k] = *(const LAS bf16x8*)(lds + PG8_SB(b, h) + boff + n * 2048 + k * 1024); } while (0)
; #define PG8_MMA(ai, bj, At, Bt) do { __builtin_amdgcn_s_setprio(1); _Pragma("unroll") for (int m = 0; m < 4; ++m) _Pragma("unroll") for (int n = 0; n < 2; ++n) _Pragma("unroll") for (int k = 0; k < 2; ++k) \
;         acc[ai][bj][m][n] = __builtin_amdgcn_mfma_f32_16x16x32_bf16(Bt[n][k], At[m][k], acc[ai][bj][m][n], 0, 0, 0); __builtin_amdgcn_s_setprio(0); } while (0)
; #define PG8_WAIT_V(n) asm volatile("s_waitcnt vmcnt(" #n ")" ::: "memory")
; #define PG8_WAIT_L(n) asm volatile("s_waitcnt lgkmcnt(" #n ")" ::: "memory")
; #define PG8_BAR __builtin_amdgcn_s_barrier()
; #define PG8_SCHED __builtin_amdgcn_sched_barrier(0)
; template <int EPI> ...
;     ...
;             PG8_WAIT_V(8); PG8_WAIT_L(0); PG8_BAR; PG8_MMA(1, 0, At, B0); PG8_MMA(1, 1, At, B1); PG8_BAR; PG8_SCHED;
;             PG8_LDB(B0, 1, 0); PG8_LDB(B1, 1, 1); PG8_SCHED; PG8_LDA(At, 1, 0); PG8_STAGE(PG8_SA(0, 1), a2 + hstep);
;             PG8_WAIT_V(8); PG8_WAIT_L(0); PG8_BAR; PG8_MMA(0, 0, At, B0); PG8_MMA(0, 1, At, B1); PG8_BAR; PG8_SCHED;
.Lup_wdone_1:
	s_waitcnt lgkmcnt(0)
	s_barrier
	s_setprio 1
	s_waitcnt lgkmcnt(0)
	v_mfma_f32_16x16x32_bf16 v[86:89], v[38:41], v[162:165], v[86:89]
	v_mfma_f32_16x16x32_bf16 v[94:97], v[46:49], v[162:165], v[94:97]
	v_mfma_f32_16x16x32_bf16 v[62:65], v[38:41], v[170:173], v[62:65]
	v_mfma_f32_16x16x32_bf16 v[78:81], v[46:49], v[170:173], v[78:81]
	v_mfma_f32_16x16x32_bf16 v[22:25], v[38:41], v[178:181], v[22:25]
	v_mfma_f32_16x16x32_bf16 v[30:33], v[46:49], v[178:181], v[30:33]
	v_mfma_f32_16x16x32_bf16 v[14:17], v[38:41], v[218:221], v[14:17]
	v_mfma_f32_16x16x32_bf16 v[10:13], v[46:49], v[218:221], v[10:13]
	v_mfma_f32_16x16x32_bf16 v[86:89], v[42:45], v[166:169], v[86:89]
	v_mfma_f32_16x16x32_bf16 v[94:97], v[50:53], v[166:169], v[94:97]
	v_mfma_f32_16x16x32_bf16 v[62:65], v[42:45], v[174:177], v[62:65]
	v_mfma_f32_16x16x32_bf16 v[78:81], v[50:53], v[174:177], v[78:81]
	v_mfma_f32_16x16x32_bf16 v[22:25], v[42:45], v[214:217], v[22:25]
	v_mfma_f32_16x16x32_bf16 v[30:33], v[50:53], v[214:217], v[30:33]
	v_mfma_f32_16x16x32_bf16 v[14:17], v[42:45], v[222:225], v[14:17]
	v_mfma_f32_16x16x32_bf16 v[10:13], v[50:53], v[222:225], v[10:13]
	v_mfma_f32_16x16x32_bf16 v[34:37], v[54:57], v[170:173], v[34:37]
	v_mfma_f32_16x16x32_bf16 v[18:21], v[54:57], v[178:181], v[18:21]
	v_mfma_f32_16x16x32_bf16 v[26:29], v[66:69], v[178:181], v[26:29]
	v_mfma_f32_16x16x32_bf16 v[6:9], v[54:57], v[218:221], v[6:9]
	v_mfma_f32_16x16x32_bf16 v[2:5], v[66:69], v[218:221], v[2:5]
	v_mfma_f32_16x16x32_bf16 v[38:41], v[54:57], v[162:165], v[82:85]
	v_mfma_f32_16x16x32_bf16 v[42:45], v[66:69], v[162:165], v[90:93]
	v_mfma_f32_16x16x32_bf16 v[34:37], v[58:61], v[174:177], v[34:37]
	v_mfma_f32_16x16x32_bf16 v[46:49], v[66:69], v[170:173], v[74:77]
	v_mfma_f32_16x16x32_bf16 v[18:21], v[58:61], v[214:217], v[18:21]
	v_mfma_f32_16x16x32_bf16 v[26:29], v[70:73], v[214:217], v[26:29]
	v_mfma_f32_16x16x32_bf16 v[6:9], v[58:61], v[222:225], v[6:9]
	v_mfma_f32_16x16x32_bf16 v[2:5], v[70:73], v[222:225], v[2:5]
	v_mfma_f32_16x16x32_bf16 v[38:41], v[58:61], v[166:169], v[38:41]
	v_mfma_f32_16x16x32_bf16 v[42:45], v[70:73], v[166:169], v[42:45]
	v_mfma_f32_16x16x32_bf16 v[46:49], v[70:73], v[174:177], v[46:49]
	s_setprio 0
	s_barrier
	s_add_i32 s84, 0, 0x18000
	s_add_i32 s85, 0, 0x1c000
	v_add_u32_e32 v66, s84, v183
	v_add_u32_e32 v74, s85, v183
	ds_read_b128 v[50:53], v66
	ds_read_b128 v[54:57], v66 offset:1024
	ds_read_b128 v[58:61], v66 offset:2048
	ds_read_b128 v[66:69], v66 offset:3072
	ds_read_b128 v[70:73], v74
	ds_read_b128 v[162:165], v74 offset:1024
	ds_read_b128 v[166:169], v74 offset:2048
	ds_read_b128 v[170:173], v74 offset:3072
	s_add_u32 s60, s60, 0x40000
	s_addc_u32 s61, s61, 0
	s_mov_b32 m0, s68
	v_lshl_add_u64 v[226:227], s[60:61], 0, v[194:195]
	ds_read_b128 v[74:77], v193 offset:32768
	ds_read_b128 v[82:85], v193 offset:33792
	ds_read_b128 v[90:93], v193 offset:34816
	ds_read_b128 v[174:177], v193 offset:35840
	ds_read_b128 v[178:181], v193 offset:36864
	ds_read_b128 v[214:217], v193 offset:37888
	ds_read_b128 v[218:221], v193 offset:38912
	ds_read_b128 v[222:225], v193 offset:39936
	global_load_lds_dwordx4 v[226:227], off
	v_lshl_add_u64 v[226:227], s[60:61], 0, v[196:197]
	s_mov_b32 m0, s69
	s_nop 0
	global_load_lds_dwordx4 v[226:227], off
	s_waitcnt vmcnt(8)
	s_waitcnt lgkmcnt(0)
	s_barrier
	s_setprio 1
	s_waitcnt lgkmcnt(0)
	v_mfma_f32_16x16x32_bf16 v[150:153], v[50:53], v[74:77], v[150:153]
	v_mfma_f32_16x16x32_bf16 v[158:161], v[58:61], v[74:77], v[158:161]
	v_mfma_f32_16x16x32_bf16 v[134:137], v[50:53], v[90:93], v[134:137]
	v_mfma_f32_16x16x32_bf16 v[142:145], v[58:61], v[90:93], v[142:145]
	v_mfma_f32_16x16x32_bf16 v[118:121], v[50:53], v[178:181], v[118:121]
	v_mfma_f32_16x16x32_bf16 v[126:129], v[58:61], v[178:181], v[126:129]
	v_mfma_f32_16x16x32_bf16 v[110:113], v[50:53], v[218:221], v[110:113]
	v_mfma_f32_16x16x32_bf16 v[106:109], v[58:61], v[218:221], v[106:109]
	v_mfma_f32_16x16x32_bf16 v[150:153], v[54:57], v[82:85], v[150:153]
	v_mfma_f32_16x16x32_bf16 v[158:161], v[66:69], v[82:85], v[158:161]
	v_mfma_f32_16x16x32_bf16 v[134:137], v[54:57], v[174:177], v[134:137]
	v_mfma_f32_16x16x32_bf16 v[142:145], v[66:69], v[174:177], v[142:145]
	v_mfma_f32_16x16x32_bf16 v[118:121], v[54:57], v[214:217], v[118:121]
	v_mfma_f32_16x16x32_bf16 v[126:129], v[66:69], v[214:217], v[126:129]
	v_mfma_f32_16x16x32_bf16 v[110:113], v[54:57], v[222:225], v[110:113]
	v_mfma_f32_16x16x32_bf16 v[106:109], v[66:69], v[222:225], v[106:109]
	v_mfma_f32_16x16x32_bf16 v[146:149], v[70:73], v[74:77], v[146:149]
	v_mfma_f32_16x16x32_bf16 v[74:77], v[166:169], v[74:77], v[154:157]
	v_mfma_f32_16x16x32_bf16 v[154:157], v[170:173], v[82:85], v[74:77]
	v_mfma_f32_16x16x32_bf16 v[74:77], v[70:73], v[90:93], v[130:133]
	v_mfma_f32_16x16x32_bf16 v[130:133], v[162:165], v[174:177], v[74:77]
	v_mfma_f32_16x16x32_bf16 v[74:77], v[166:169], v[90:93], v[138:141]
	v_mfma_f32_16x16x32_bf16 v[138:141], v[170:173], v[174:177], v[74:77]
	v_mfma_f32_16x16x32_bf16 v[74:77], v[70:73], v[178:181], v[114:117]
	v_mfma_f32_16x16x32_bf16 v[114:117], v[162:165], v[214:217], v[74:77]
	v_mfma_f32_16x16x32_bf16 v[74:77], v[166:169], v[178:181], v[122:125]
	v_mfma_f32_16x16x32_bf16 v[122:125], v[170:173], v[214:217], v[74:77]
	v_mfma_f32_16x16x32_bf16 v[74:77], v[70:73], v[218:221], v[102:105]
	v_mfma_f32_16x16x32_bf16 v[102:105], v[162:165], v[222:225], v[74:77]
	v_mfma_f32_16x16x32_bf16 v[74:77], v[166:169], v[218:221], v[98:101]
	v_mfma_f32_16x16x32_bf16 v[146:149], v[162:165], v[82:85], v[146:149]
	v_mfma_f32_16x16x32_bf16 v[98:101], v[170:173], v[222:225], v[74:77]
	s_setprio 0
	s_barrier
; #define PG8_STAGE(bufoff, gbase) do { _Pragma("unroll") for (int _i = 0; _i < 2; ++_i) \
;         __builtin_amdgcn_global_load_lds((const unsigned*)((const char*)(gbase) + voff[_i]), (LAS unsigned*)(lds + (bufoff) + ldsw + _i * 8192), 16, 0, 0); } while (0)
; #define PG8_LDA(dst, b, h) do { _Pragma("unroll") for (int m = 0; m < 4; ++m) _Pragma("unroll") for (int k = 0; k < 2; ++k) dst[m][k] = *(const LAS bf16x8*)(lds + PG8_SA(b, h) + aoff + m * 2048 + k * 1024); } while (0)
; #define PG8_MMA(ai, bj, At, Bt) do { __builtin_amdgcn_s_setprio(1); _Pragma("unroll") for (int m = 0; m < 4; ++m) _Pragma("unroll") for (int n = 0; n < 2; ++n) _Pragma("unroll") for (int k = 0; k < 2; ++k) \
;         acc[ai][bj][m][n] = __builtin_amdgcn_mfma_f32_16x16x32_bf16(Bt[n][k], At[m][k], acc[ai][bj][m][n], 0, 0, 0); __builtin_amdgcn_s_setprio(0); } while (0)
; #define PG8_WAIT_V(n) asm volatile("s_waitcnt vmcnt(" #n ")" ::: "memory")
; #define PG8_WAIT_L(n) asm volatile("s_waitcnt lgkmcnt(" #n ")" ::: "memory")
; #define PG8_BAR __builtin_amdgcn_s_barrier()
; #define PG8_SCHED __builtin_amdgcn_sched_barrier(0)
; template <int EPI> ...
;     ...
;             PG8_LDA(At, 1, 1); PG8_STAGE(PG8_SB(1, 0), b3); PG8_STAGE(PG8_SB(1, 1), b3 + hstep); PG8_STAGE(PG8_SA(1, 0), a3);
;             PG8_WAIT_V(8); PG8_WAIT_L(0); PG8_BAR; PG8_MMA(1, 0, At, B0); PG8_MMA(1, 1, At, B1); PG8_BAR; PG8_SCHED;
;         }
;         if (wr == 0) PG8_BAR;
	s_add_i32 s60, s84, s65
	v_lshl_add_u64 v[82:83], v[230:231], 0, s[26:27]
	s_mov_b32 m0, s60
	s_nop 0
	ds_read_b128 v[74:77], v193 offset:49152
	ds_read_b128 v[90:93], v193 offset:50176
	ds_read_b128 v[174:177], v193 offset:51200
	ds_read_b128 v[178:181], v193 offset:52224
	ds_read_b128 v[214:217], v193 offset:53248
	ds_read_b128 v[218:221], v193 offset:54272
	ds_read_b128 v[222:225], v193 offset:55296
	ds_read_b128 v[226:229], v193 offset:56320
	global_load_lds_dwordx4 v[82:83], off
	s_add_i32 m0, s60, 0x2000
	s_add_u32 s58, s58, 0x40080
	v_lshl_add_u64 v[82:83], v[232:233], 0, s[26:27]
	s_addc_u32 s59, s59, 0
	s_add_i32 s60, s85, s65
	global_load_lds_dwordx4 v[82:83], off
	v_lshl_add_u64 v[82:83], s[58:59], 0, v[194:195]
	s_mov_b32 m0, s60
	s_nop 0
	global_load_lds_dwordx4 v[82:83], off
	v_lshl_add_u64 v[82:83], s[58:59], 0, v[196:197]
	s_add_i32 m0, s60, 0x2000
	s_nop 0
	global_load_lds_dwordx4 v[82:83], off
	v_lshl_add_u64 v[82:83], v[234:235], 0, s[26:27]
	s_mov_b32 m0, s72
	s_nop 0
	global_load_lds_dwordx4 v[82:83], off
	v_lshl_add_u64 v[82:83], v[236:237], 0, s[26:27]
	s_mov_b32 m0, s73
	s_nop 0
	global_load_lds_dwordx4 v[82:83], off
	s_waitcnt vmcnt(8)
	s_waitcnt lgkmcnt(0)
	s_barrier
	s_setprio 1
	s_waitcnt lgkmcnt(0)
	v_mfma_f32_16x16x32_bf16 v[82:85], v[50:53], v[74:77], v[86:89]
	v_mfma_f32_16x16x32_bf16 v[86:89], v[54:57], v[90:93], v[82:85]
	v_mfma_f32_16x16x32_bf16 v[82:85], v[58:61], v[74:77], v[94:97]
	v_mfma_f32_16x16x32_bf16 v[62:65], v[50:53], v[174:177], v[62:65]
	v_mfma_f32_16x16x32_bf16 v[78:81], v[58:61], v[174:177], v[78:81]
	v_mfma_f32_16x16x32_bf16 v[22:25], v[50:53], v[214:217], v[22:25]
	v_mfma_f32_16x16x32_bf16 v[30:33], v[58:61], v[214:217], v[30:33]
	v_mfma_f32_16x16x32_bf16 v[14:17], v[50:53], v[222:225], v[14:17]
	v_mfma_f32_16x16x32_bf16 v[10:13], v[58:61], v[222:225], v[10:13]
	v_mfma_f32_16x16x32_bf16 v[94:97], v[66:69], v[90:93], v[82:85]
	v_mfma_f32_16x16x32_bf16 v[62:65], v[54:57], v[178:181], v[62:65]
	v_mfma_f32_16x16x32_bf16 v[78:81], v[66:69], v[178:181], v[78:81]
	v_mfma_f32_16x16x32_bf16 v[22:25], v[54:57], v[218:221], v[22:25]
	v_mfma_f32_16x16x32_bf16 v[30:33], v[66:69], v[218:221], v[30:33]
	v_mfma_f32_16x16x32_bf16 v[14:17], v[54:57], v[226:229], v[14:17]
	v_mfma_f32_16x16x32_bf16 v[10:13], v[66:69], v[226:229], v[10:13]
	v_mfma_f32_16x16x32_bf16 v[38:41], v[70:73], v[74:77], v[38:41]
	v_mfma_f32_16x16x32_bf16 v[82:85], v[162:165], v[90:93], v[38:41]
	v_mfma_f32_16x16x32_bf16 v[38:41], v[166:169], v[74:77], v[42:45]
	v_mfma_f32_16x16x32_bf16 v[90:93], v[170:173], v[90:93], v[38:41]
	v_mfma_f32_16x16x32_bf16 v[34:37], v[70:73], v[174:177], v[34:37]
	v_mfma_f32_16x16x32_bf16 v[38:41], v[166:169], v[174:177], v[46:49]
	v_mfma_f32_16x16x32_bf16 v[18:21], v[70:73], v[214:217], v[18:21]
	v_mfma_f32_16x16x32_bf16 v[26:29], v[166:169], v[214:217], v[26:29]
	v_mfma_f32_16x16x32_bf16 v[6:9], v[70:73], v[222:225], v[6:9]
	v_mfma_f32_16x16x32_bf16 v[2:5], v[166:169], v[222:225], v[2:5]
	v_mfma_f32_16x16x32_bf16 v[34:37], v[162:165], v[178:181], v[34:37]
	v_mfma_f32_16x16x32_bf16 v[74:77], v[170:173], v[178:181], v[38:41]
	v_mfma_f32_16x16x32_bf16 v[18:21], v[162:165], v[218:221], v[18:21]
	v_mfma_f32_16x16x32_bf16 v[26:29], v[170:173], v[218:221], v[26:29]
	v_mfma_f32_16x16x32_bf16 v[6:9], v[162:165], v[226:229], v[6:9]
	v_mfma_f32_16x16x32_bf16 v[2:5], v[170:173], v[226:229], v[2:5]
	s_setprio 0
	s_barrier
	s_add_i32 s83, s83, 2
	s_add_u32 s56, s56, 0x100
	s_addc_u32 s57, s57, 0
	s_add_u32 s62, s62, 0x100
	s_addc_u32 s63, s63, 0
	s_cmp_gt_u32 s83, 13
	s_cbranch_scc0 .LBB0_970
	s_and_b64 vcc, exec, s[28:29]
	s_cbranch_vccz .LBB0_973
	s_barrier

; #define PG8_STAGE(bufoff, gbase) do { _Pragma("unroll") for (int _i = 0; _i < 2; ++_i) \
;         __builtin_amdgcn_global_load_lds((const unsigned*)((const char*)(gbase) + voff[_i]), (LAS unsigned*)(lds + (bufoff) + ldsw + _i * 8192), 16, 0, 0); } while (0)
; #define PG8_LDA(dst, b, h) do { _Pragma("unroll") for (int m = 0; m < 4; ++m) _Pragma("unroll") for (int k = 0; k < 2; ++k) dst[m][k] = *(const LAS bf16x8*)(lds + PG8_SA(b, h) + aoff + m * 2048 + k * 1024); } while (0)
; #define PG8_LDB(dst, b, h) do { _Pragma("unroll") for (int n = 0; n < 2; ++n) _Pragma("unroll") for (int k = 0; k < 2; ++k) dst[n][k] = *(const LAS bf16x8*)(lds + PG8_SB(b, h) + boff + n * 2048 + k * 1024); } while (0)
; #define PG8_MMA(ai, bj, At, Bt) do { __builtin_amdgcn_s_setprio(1); _Pragma("unroll") for (int m = 0; m < 4; ++m) _Pragma("unroll") for (int n = 0; n < 2; ++n) _Pragma("unroll") for (int k = 0; k < 2; ++k) \
;         acc[ai][bj][m][n] = __builtin_amdgcn_mfma_f32_16x16x32_bf16(Bt[n][k], At[m][k], acc[ai][bj][m][n], 0, 0, 0); __builtin_amdgcn_s_setprio(0); } while (0)
; #define PG8_WAIT_V(n) asm volatile("s_waitcnt vmcnt(" #n ")" ::: "memory")
; #define PG8_WAIT_L(n) asm volatile("s_waitcnt lgkmcnt(" #n ")" ::: "memory")
; #define PG8_BAR __builtin_amdgcn_s_barrier()
; #define PG8_SCHED __builtin_amdgcn_sched_barrier(0)
; template <int EPI> ...
;     ...
;         for (int t = 0; t < cnk; t += 2) {
;             const bool last = (t == cnk - 2);
;             const char* a1 = cA + (size_t)(t + 1) * kstep;
;             const char* a2 = last ? nA : cA + (size_t)(t + 2) * kstep; const char* b2 = last ? nB : cB + (size_t)(t + 2) * kstep;
;             const char* a3 = a2 + kstep; const char* b3 = b2 + kstep;
;             PG8_LDB(B0, 0, 0); PG8_LDB(B1, 0, 1); PG8_SCHED; PG8_LDA(At, 0, 0); PG8_STAGE(PG8_SA(1, 1), a1 + hstep);
;             PG8_WAIT_V(8); PG8_WAIT_L(0); PG8_BAR; PG8_MMA(0, 0, At, B0); PG8_MMA(0, 1, At, B1); PG8_BAR; PG8_SCHED;
;             PG8_LDA(At, 0, 1); PG8_STAGE(PG8_SB(0, 0), b2); PG8_STAGE(PG8_SB(0, 1), b2 + hstep); PG8_STAGE(PG8_SA(0, 0), a2);
;             PG8_WAIT_V(8); PG8_WAIT_L(0); PG8_BAR; PG8_MMA(1, 0, At, B0); PG8_MMA(1, 1, At, B1); PG8_BAR; PG8_SCHED;
.LBB0_1246:
	ds_read_b128 v[128:131], v156
	ds_read_b128 v[132:135], v156 offset:1024
	ds_read_b128 v[148:151], v156 offset:2048
	ds_read_b128 v[160:163], v156 offset:3072
	ds_read_b128 v[164:167], v157
	ds_read_b128 v[168:171], v157 offset:1024
	ds_read_b128 v[172:175], v157 offset:2048
	ds_read_b128 v[176:179], v157 offset:3072
	s_add_i32 s57, s28, 2
	s_add_u32 s26, s24, 0x100
	s_addc_u32 s27, s25, 0
	s_cmp_eq_u32 s54, s28
	s_cselect_b32 s28, s18, s55
	s_cselect_b32 s31, s17, s27
	s_cselect_b32 s30, s16, s26
	s_cselect_b32 s29, s19, s56
	v_lshl_add_u64 v[180:181], s[24:25], 0, v[142:143]
	s_add_i32 m0, s38, 0xc000
	ds_read_b128 v[194:197], v158
	ds_read_b128 v[198:201], v158 offset:1024
	ds_read_b128 v[202:205], v158 offset:2048
	ds_read_b128 v[206:209], v158 offset:3072
	ds_read_b128 v[210:213], v158 offset:4096
	ds_read_b128 v[214:217], v158 offset:5120
	ds_read_b128 v[218:221], v158 offset:6144
	ds_read_b128 v[222:225], v158 offset:7168
	global_load_lds_dwordx4 v[180:181], off
	v_lshl_add_u64 v[180:181], s[24:25], 0, v[144:145]
	s_add_i32 m0, s38, 0xe000
	s_nop 0
	global_load_lds_dwordx4 v[180:181], off
	s_waitcnt vmcnt(8)
	s_waitcnt lgkmcnt(0)
	s_barrier
	s_setprio 1
	s_waitcnt lgkmcnt(0)
	v_mfma_f32_16x16x32_bf16 v[124:127], v[128:131], v[194:197], v[124:127]
	v_mfma_f32_16x16x32_bf16 v[120:123], v[148:151], v[194:197], v[120:123]
	v_mfma_f32_16x16x32_bf16 v[116:119], v[128:131], v[202:205], v[116:119]
	v_mfma_f32_16x16x32_bf16 v[112:115], v[148:151], v[202:205], v[112:115]
	v_mfma_f32_16x16x32_bf16 v[104:107], v[128:131], v[210:213], v[104:107]
	v_mfma_f32_16x16x32_bf16 v[96:99], v[148:151], v[210:213], v[96:99]
	v_mfma_f32_16x16x32_bf16 v[88:91], v[128:131], v[218:221], v[88:91]
	v_mfma_f32_16x16x32_bf16 v[80:83], v[148:151], v[218:221], v[80:83]
	v_mfma_f32_16x16x32_bf16 v[124:127], v[132:135], v[198:201], v[124:127]
	v_mfma_f32_16x16x32_bf16 v[120:123], v[160:163], v[198:201], v[120:123]
	v_mfma_f32_16x16x32_bf16 v[116:119], v[132:135], v[206:209], v[116:119]
	v_mfma_f32_16x16x32_bf16 v[112:115], v[160:163], v[206:209], v[112:115]
	v_mfma_f32_16x16x32_bf16 v[104:107], v[132:135], v[214:217], v[104:107]
	v_mfma_f32_16x16x32_bf16 v[96:99], v[160:163], v[214:217], v[96:99]
	v_mfma_f32_16x16x32_bf16 v[88:91], v[132:135], v[222:225], v[88:91]
	v_mfma_f32_16x16x32_bf16 v[80:83], v[160:163], v[222:225], v[80:83]
	v_mfma_f32_16x16x32_bf16 v[108:111], v[164:167], v[194:197], v[108:111]
	v_mfma_f32_16x16x32_bf16 v[100:103], v[172:175], v[194:197], v[100:103]
	v_mfma_f32_16x16x32_bf16 v[92:95], v[164:167], v[202:205], v[92:95]
	v_mfma_f32_16x16x32_bf16 v[84:87], v[172:175], v[202:205], v[84:87]
	v_mfma_f32_16x16x32_bf16 v[76:79], v[164:167], v[210:213], v[76:79]
	v_mfma_f32_16x16x32_bf16 v[72:75], v[172:175], v[210:213], v[72:75]
	v_mfma_f32_16x16x32_bf16 v[68:71], v[164:167], v[218:221], v[68:71]
	v_mfma_f32_16x16x32_bf16 v[64:67], v[172:175], v[218:221], v[64:67]
	v_mfma_f32_16x16x32_bf16 v[108:111], v[168:171], v[198:201], v[108:111]
	v_mfma_f32_16x16x32_bf16 v[100:103], v[176:179], v[198:201], v[100:103]
	v_mfma_f32_16x16x32_bf16 v[92:95], v[168:171], v[206:209], v[92:95]
	v_mfma_f32_16x16x32_bf16 v[84:87], v[176:179], v[206:209], v[84:87]
	v_mfma_f32_16x16x32_bf16 v[76:79], v[168:171], v[214:217], v[76:79]
	v_mfma_f32_16x16x32_bf16 v[72:75], v[176:179], v[214:217], v[72:75]
	v_mfma_f32_16x16x32_bf16 v[68:71], v[168:171], v[222:225], v[68:71]
	v_mfma_f32_16x16x32_bf16 v[64:67], v[176:179], v[222:225], v[64:67]
	s_setprio 0
	s_barrier
	s_add_i32 s24, s45, s37
	v_lshl_add_u64 v[180:181], s[28:29], 0, v[136:137]
	s_mov_b32 m0, s24
	ds_read_b128 v[194:197], v158 offset:16384
	ds_read_b128 v[198:201], v158 offset:17408
	ds_read_b128 v[202:205], v158 offset:18432
	ds_read_b128 v[206:209], v158 offset:19456
	ds_read_b128 v[210:213], v158 offset:20480
	ds_read_b128 v[214:217], v158 offset:21504
	ds_read_b128 v[218:221], v158 offset:22528
	ds_read_b128 v[222:225], v158 offset:23552
	global_load_lds_dwordx4 v[180:181], off
	s_add_i32 m0, s24, 0x2000
	s_add_u32 s24, s28, 0xb0000
	v_lshl_add_u64 v[186:187], s[28:29], 0, v[138:139]
	s_addc_u32 s25, s29, 0
	s_add_i32 s58, s46, s37
	global_load_lds_dwordx4 v[186:187], off
	v_lshl_add_u64 v[226:227], s[24:25], 0, v[136:137]
	s_mov_b32 m0, s58
	v_lshl_add_u64 v[228:229], s[30:31], 0, v[138:139]
	global_load_lds_dwordx4 v[226:227], off
	v_lshl_add_u64 v[226:227], s[24:25], 0, v[138:139]
	s_add_i32 m0, s58, 0x2000
	s_nop 0
	global_load_lds_dwordx4 v[226:227], off
	v_lshl_add_u64 v[226:227], s[30:31], 0, v[136:137]
	s_mov_b32 m0, s38
	s_nop 0
	global_load_lds_dwordx4 v[226:227], off
	s_mov_b32 m0, s39
	s_nop 0
	global_load_lds_dwordx4 v[228:229], off
	s_waitcnt vmcnt(8)
	s_waitcnt lgkmcnt(0)
	s_barrier
; #define PG8_STAGE(bufoff, gbase) do { _Pragma("unroll") for (int _i = 0; _i < 2; ++_i) \
;         __builtin_amdgcn_global_load_lds((const unsigned*)((const char*)(gbase) + voff[_i]), (LAS unsigned*)(lds + (bufoff) + ldsw + _i * 8192), 16, 0, 0); } while (0)
; #define PG8_LDA(dst, b, h) do { _Pragma("unroll") for (int m = 0; m < 4; ++m) _Pragma("unroll") for (int k = 0; k < 2; ++k) dst[m][k] = *(const LAS bf16x8*)(lds + PG8_SA(b, h) + aoff + m * 2048 + k * 1024); } while (0)
; #define PG8_LDB(dst, b, h) do { _Pragma("unroll") for (int n = 0; n < 2; ++n) _Pragma("unroll") for (int k = 0; k < 2; ++k) dst[n][k] = *(const LAS bf16x8*)(lds + PG8_SB(b, h) + boff + n * 2048 + k * 1024); } while (0)
; #define PG8_MMA(ai, bj, At, Bt) do { __builtin_amdgcn_s_setprio(1); _Pragma("unroll") for (int m = 0; m < 4; ++m) _Pragma("unroll") for (int n = 0; n < 2; ++n) _Pragma("unroll") for (int k = 0; k < 2; ++k) \
;         acc[ai][bj][m][n] = __builtin_amdgcn_mfma_f32_16x16x32_bf16(Bt[n][k], At[m][k], acc[ai][bj][m][n], 0, 0, 0); __builtin_amdgcn_s_setprio(0); } while (0)
; #define PG8_WAIT_V(n) asm volatile("s_waitcnt vmcnt(" #n ")" ::: "memory")
; #define PG8_WAIT_L(n) asm volatile("s_waitcnt lgkmcnt(" #n ")" ::: "memory")
; #define PG8_BAR __builtin_amdgcn_s_barrier()
; #define PG8_SCHED __builtin_amdgcn_sched_barrier(0)
; template <int EPI> ...
;     ...
;             PG8_WAIT_V(8); PG8_WAIT_L(0); PG8_BAR; PG8_MMA(1, 0, At, B0); PG8_MMA(1, 1, At, B1); PG8_BAR; PG8_SCHED;
;             PG8_LDB(B0, 1, 0); PG8_LDB(B1, 1, 1); PG8_SCHED; PG8_LDA(At, 1, 0); PG8_STAGE(PG8_SA(0, 1), a2 + hstep);
;             PG8_WAIT_V(8); PG8_WAIT_L(0); PG8_BAR; PG8_MMA(0, 0, At, B0); PG8_MMA(0, 1, At, B1); PG8_BAR; PG8_SCHED;
	s_setprio 1
	s_waitcnt lgkmcnt(0)
	v_mfma_f32_16x16x32_bf16 v[60:63], v[128:131], v[194:197], v[60:63]
	v_mfma_f32_16x16x32_bf16 v[56:59], v[148:151], v[194:197], v[56:59]
	v_mfma_f32_16x16x32_bf16 v[52:55], v[128:131], v[202:205], v[52:55]
	v_mfma_f32_16x16x32_bf16 v[48:51], v[148:151], v[202:205], v[48:51]
	v_mfma_f32_16x16x32_bf16 v[40:43], v[128:131], v[210:213], v[40:43]
	v_mfma_f32_16x16x32_bf16 v[32:35], v[148:151], v[210:213], v[32:35]
	v_mfma_f32_16x16x32_bf16 v[24:27], v[128:131], v[218:221], v[24:27]
	v_mfma_f32_16x16x32_bf16 v[16:19], v[148:151], v[218:221], v[16:19]
	v_mfma_f32_16x16x32_bf16 v[60:63], v[132:135], v[198:201], v[60:63]
	v_mfma_f32_16x16x32_bf16 v[56:59], v[160:163], v[198:201], v[56:59]
	v_mfma_f32_16x16x32_bf16 v[52:55], v[132:135], v[206:209], v[52:55]
	v_mfma_f32_16x16x32_bf16 v[48:51], v[160:163], v[206:209], v[48:51]
	v_mfma_f32_16x16x32_bf16 v[40:43], v[132:135], v[214:217], v[40:43]
	v_mfma_f32_16x16x32_bf16 v[32:35], v[160:163], v[214:217], v[32:35]
	v_mfma_f32_16x16x32_bf16 v[24:27], v[132:135], v[222:225], v[24:27]
	v_mfma_f32_16x16x32_bf16 v[16:19], v[160:163], v[222:225], v[16:19]
	v_mfma_f32_16x16x32_bf16 v[44:47], v[164:167], v[194:197], v[44:47]
	v_mfma_f32_16x16x32_bf16 v[36:39], v[172:175], v[194:197], v[36:39]
	v_mfma_f32_16x16x32_bf16 v[28:31], v[164:167], v[202:205], v[28:31]
	v_mfma_f32_16x16x32_bf16 v[20:23], v[172:175], v[202:205], v[20:23]
	v_mfma_f32_16x16x32_bf16 v[12:15], v[164:167], v[210:213], v[12:15]
	v_mfma_f32_16x16x32_bf16 v[8:11], v[172:175], v[210:213], v[8:11]
	v_mfma_f32_16x16x32_bf16 v[4:7], v[164:167], v[218:221], v[4:7]
	v_mfma_f32_16x16x32_bf16 v[0:3], v[172:175], v[218:221], v[0:3]
	v_mfma_f32_16x16x32_bf16 v[44:47], v[168:171], v[198:201], v[44:47]
	v_mfma_f32_16x16x32_bf16 v[36:39], v[176:179], v[198:201], v[36:39]
	v_mfma_f32_16x16x32_bf16 v[28:31], v[168:171], v[206:209], v[28:31]
	v_mfma_f32_16x16x32_bf16 v[20:23], v[176:179], v[206:209], v[20:23]
	v_mfma_f32_16x16x32_bf16 v[12:15], v[168:171], v[214:217], v[12:15]
	v_mfma_f32_16x16x32_bf16 v[8:11], v[176:179], v[214:217], v[8:11]
	v_mfma_f32_16x16x32_bf16 v[4:7], v[168:171], v[222:225], v[4:7]
	v_mfma_f32_16x16x32_bf16 v[0:3], v[176:179], v[222:225], v[0:3]
	s_setprio 0
	s_barrier
	s_add_i32 s58, 0, 0x18000
	v_add_u32_e32 v159, s58, v153
	s_add_i32 s59, 0, 0x1c000
	ds_read_b128 v[128:131], v159
	ds_read_b128 v[132:135], v159 offset:1024
	ds_read_b128 v[148:151], v159 offset:2048
	ds_read_b128 v[160:163], v159 offset:3072
	v_add_u32_e32 v159, s59, v153
	ds_read_b128 v[164:167], v159
	ds_read_b128 v[168:171], v159 offset:1024
	ds_read_b128 v[172:175], v159 offset:2048
	ds_read_b128 v[176:179], v159 offset:3072
	s_add_u32 s24, s30, 0xb0000
	s_addc_u32 s25, s31, 0
	s_mov_b32 m0, s40
	v_lshl_add_u64 v[230:231], s[24:25], 0, v[136:137]
	ds_read_b128 v[194:197], v158 offset:32768
	ds_read_b128 v[198:201], v158 offset:33792
	ds_read_b128 v[202:205], v158 offset:34816
	ds_read_b128 v[206:209], v158 offset:35840
	ds_read_b128 v[210:213], v158 offset:36864
	ds_read_b128 v[214:217], v158 offset:37888
	ds_read_b128 v[218:221], v158 offset:38912
	ds_read_b128 v[222:225], v158 offset:39936
	global_load_lds_dwordx4 v[230:231], off
	v_lshl_add_u64 v[230:231], s[24:25], 0, v[138:139]
	s_mov_b32 m0, s41
	s_nop 0
	global_load_lds_dwordx4 v[230:231], off
	s_waitcnt vmcnt(8)
	s_waitcnt lgkmcnt(0)
	s_barrier
	s_setprio 1
	s_waitcnt lgkmcnt(0)
	v_mfma_f32_16x16x32_bf16 v[124:127], v[128:131], v[194:197], v[124:127]
	v_mfma_f32_16x16x32_bf16 v[120:123], v[148:151], v[194:197], v[120:123]
	v_mfma_f32_16x16x32_bf16 v[116:119], v[128:131], v[202:205], v[116:119]
	v_mfma_f32_16x16x32_bf16 v[112:115], v[148:151], v[202:205], v[112:115]
	v_mfma_f32_16x16x32_bf16 v[104:107], v[128:131], v[210:213], v[104:107]
	v_mfma_f32_16x16x32_bf16 v[96:99], v[148:151], v[210:213], v[96:99]
	v_mfma_f32_16x16x32_bf16 v[88:91], v[128:131], v[218:221], v[88:91]
	v_mfma_f32_16x16x32_bf16 v[80:83], v[148:151], v[218:221], v[80:83]
	v_mfma_f32_16x16x32_bf16 v[124:127], v[132:135], v[198:201], v[124:127]
	v_mfma_f32_16x16x32_bf16 v[120:123], v[160:163], v[198:201], v[120:123]
	v_mfma_f32_16x16x32_bf16 v[116:119], v[132:135], v[206:209], v[116:119]
	v_mfma_f32_16x16x32_bf16 v[112:115], v[160:163], v[206:209], v[112:115]
	v_mfma_f32_16x16x32_bf16 v[104:107], v[132:135], v[214:217], v[104:107]
	v_mfma_f32_16x16x32_bf16 v[96:99], v[160:163], v[214:217], v[96:99]
	v_mfma_f32_16x16x32_bf16 v[88:91], v[132:135], v[222:225], v[88:91]
	v_mfma_f32_16x16x32_bf16 v[80:83], v[160:163], v[222:225], v[80:83]
	v_mfma_f32_16x16x32_bf16 v[108:111], v[164:167], v[194:197], v[108:111]
	v_mfma_f32_16x16x32_bf16 v[100:103], v[172:175], v[194:197], v[100:103]
	v_mfma_f32_16x16x32_bf16 v[92:95], v[164:167], v[202:205], v[92:95]
	v_mfma_f32_16x16x32_bf16 v[84:87], v[172:175], v[202:205], v[84:87]
	v_mfma_f32_16x16x32_bf16 v[76:79], v[164:167], v[210:213], v[76:79]
	v_mfma_f32_16x16x32_bf16 v[72:75], v[172:175], v[210:213], v[72:75]
	v_mfma_f32_16x16x32_bf16 v[68:71], v[164:167], v[218:221], v[68:71]
	v_mfma_f32_16x16x32_bf16 v[64:67], v[172:175], v[218:221], v[64:67]
	v_mfma_f32_16x16x32_bf16 v[108:111], v[168:171], v[198:201], v[108:111]
	v_mfma_f32_16x16x32_bf16 v[100:103], v[176:179], v[198:201], v[100:103]
	v_mfma_f32_16x16x32_bf16 v[92:95], v[168:171], v[206:209], v[92:95]
	v_mfma_f32_16x16x32_bf16 v[84:87], v[176:179], v[206:209], v[84:87]
	v_mfma_f32_16x16x32_bf16 v[76:79], v[168:171], v[214:217], v[76:79]
	v_mfma_f32_16x16x32_bf16 v[72:75], v[176:179], v[214:217], v[72:75]
	v_mfma_f32_16x16x32_bf16 v[68:71], v[168:171], v[222:225], v[68:71]
	v_mfma_f32_16x16x32_bf16 v[64:67], v[176:179], v[222:225], v[64:67]
	s_setprio 0
	s_barrier
; #define PG8_STAGE(bufoff, gbase) do { _Pragma("unroll") for (int _i = 0; _i < 2; ++_i) \
;         __builtin_amdgcn_global_load_lds((const unsigned*)((const char*)(gbase) + voff[_i]), (LAS unsigned*)(lds + (bufoff) + ldsw + _i * 8192), 16, 0, 0); } while (0)
; #define PG8_LDA(dst, b, h) do { _Pragma("unroll") for (int m = 0; m < 4; ++m) _Pragma("unroll") for (int k = 0; k < 2; ++k) dst[m][k] = *(const LAS bf16x8*)(lds + PG8_SA(b, h) + aoff + m * 2048 + k * 1024); } while (0)
; #define PG8_MMA(ai, bj, At, Bt) do { __builtin_amdgcn_s_setprio(1); _Pragma("unroll") for (int m = 0; m < 4; ++m) _Pragma("unroll") for (int n = 0; n < 2; ++n) _Pragma("unroll") for (int k = 0; k < 2; ++k) \
;         acc[ai][bj][m][n] = __builtin_amdgcn_mfma_f32_16x16x32_bf16(Bt[n][k], At[m][k], acc[ai][bj][m][n], 0, 0, 0); __builtin_amdgcn_s_setprio(0); } while (0)
; #define PG8_WAIT_V(n) asm volatile("s_waitcnt vmcnt(" #n ")" ::: "memory")
; #define PG8_WAIT_L(n) asm volatile("s_waitcnt lgkmcnt(" #n ")" ::: "memory")
; #define PG8_BAR __builtin_amdgcn_s_barrier()
; #define PG8_SCHED __builtin_amdgcn_sched_barrier(0)
; template <int EPI> ...
;     ...
;             PG8_LDA(At, 1, 1); PG8_STAGE(PG8_SB(1, 0), b3); PG8_STAGE(PG8_SB(1, 1), b3 + hstep); PG8_STAGE(PG8_SA(1, 0), a3);
;             PG8_WAIT_V(8); PG8_WAIT_L(0); PG8_BAR; PG8_MMA(1, 0, At, B0); PG8_MMA(1, 1, At, B1); PG8_BAR; PG8_SCHED;
;         }
;         if (wr == 0) PG8_BAR;
;         if (SPLIT && cur_slice >= 0) {
	s_add_i32 s24, s58, s37
	v_lshl_add_u64 v[180:181], v[180:181], 0, s[10:11]
	s_mov_b32 m0, s24
	ds_read_b128 v[194:197], v158 offset:49152
	ds_read_b128 v[198:201], v158 offset:50176
	ds_read_b128 v[202:205], v158 offset:51200
	ds_read_b128 v[206:209], v158 offset:52224
	ds_read_b128 v[210:213], v158 offset:53248
	ds_read_b128 v[214:217], v158 offset:54272
	ds_read_b128 v[218:221], v158 offset:55296
	ds_read_b128 v[222:225], v158 offset:56320
	global_load_lds_dwordx4 v[180:181], off
	s_add_i32 m0, s24, 0x2000
	s_add_u32 s24, s28, 0xb0080
	v_lshl_add_u64 v[180:181], v[186:187], 0, s[10:11]
	s_addc_u32 s25, s29, 0
	s_add_i32 s28, s59, s37
	global_load_lds_dwordx4 v[180:181], off
	v_lshl_add_u64 v[180:181], s[24:25], 0, v[136:137]
	s_mov_b32 m0, s28
	s_nop 0
	global_load_lds_dwordx4 v[180:181], off
	v_lshl_add_u64 v[180:181], s[24:25], 0, v[138:139]
	s_add_i32 m0, s28, 0x2000
	s_nop 0
	global_load_lds_dwordx4 v[180:181], off
	v_lshl_add_u64 v[180:181], v[226:227], 0, s[10:11]
	s_mov_b32 m0, s42
	s_nop 0
	global_load_lds_dwordx4 v[180:181], off
	v_lshl_add_u64 v[180:181], v[228:229], 0, s[10:11]
	s_mov_b32 m0, s43
	s_nop 0
	global_load_lds_dwordx4 v[180:181], off
	s_waitcnt vmcnt(8)
	s_waitcnt lgkmcnt(0)
	s_barrier
	s_setprio 1
	s_waitcnt lgkmcnt(0)
	v_mfma_f32_16x16x32_bf16 v[60:63], v[128:131], v[194:197], v[60:63]
	v_mfma_f32_16x16x32_bf16 v[56:59], v[148:151], v[194:197], v[56:59]
	v_mfma_f32_16x16x32_bf16 v[52:55], v[128:131], v[202:205], v[52:55]
	v_mfma_f32_16x16x32_bf16 v[48:51], v[148:151], v[202:205], v[48:51]
	v_mfma_f32_16x16x32_bf16 v[40:43], v[128:131], v[210:213], v[40:43]
	v_mfma_f32_16x16x32_bf16 v[32:35], v[148:151], v[210:213], v[32:35]
	v_mfma_f32_16x16x32_bf16 v[24:27], v[128:131], v[218:221], v[24:27]
	v_mfma_f32_16x16x32_bf16 v[16:19], v[148:151], v[218:221], v[16:19]
	v_mfma_f32_16x16x32_bf16 v[60:63], v[132:135], v[198:201], v[60:63]
	v_mfma_f32_16x16x32_bf16 v[56:59], v[160:163], v[198:201], v[56:59]
	v_mfma_f32_16x16x32_bf16 v[52:55], v[132:135], v[206:209], v[52:55]
	v_mfma_f32_16x16x32_bf16 v[48:51], v[160:163], v[206:209], v[48:51]
	v_mfma_f32_16x16x32_bf16 v[40:43], v[132:135], v[214:217], v[40:43]
	v_mfma_f32_16x16x32_bf16 v[32:35], v[160:163], v[214:217], v[32:35]
	v_mfma_f32_16x16x32_bf16 v[24:27], v[132:135], v[222:225], v[24:27]
	v_mfma_f32_16x16x32_bf16 v[16:19], v[160:163], v[222:225], v[16:19]
	v_mfma_f32_16x16x32_bf16 v[44:47], v[164:167], v[194:197], v[44:47]
	v_mfma_f32_16x16x32_bf16 v[36:39], v[172:175], v[194:197], v[36:39]
	v_mfma_f32_16x16x32_bf16 v[28:31], v[164:167], v[202:205], v[28:31]
	v_mfma_f32_16x16x32_bf16 v[20:23], v[172:175], v[202:205], v[20:23]
	v_mfma_f32_16x16x32_bf16 v[12:15], v[164:167], v[210:213], v[12:15]
	v_mfma_f32_16x16x32_bf16 v[8:11], v[172:175], v[210:213], v[8:11]
	v_mfma_f32_16x16x32_bf16 v[4:7], v[164:167], v[218:221], v[4:7]
	v_mfma_f32_16x16x32_bf16 v[0:3], v[172:175], v[218:221], v[0:3]
	v_mfma_f32_16x16x32_bf16 v[44:47], v[168:171], v[198:201], v[44:47]
	v_mfma_f32_16x16x32_bf16 v[36:39], v[176:179], v[198:201], v[36:39]
	v_mfma_f32_16x16x32_bf16 v[28:31], v[168:171], v[206:209], v[28:31]
	v_mfma_f32_16x16x32_bf16 v[20:23], v[176:179], v[206:209], v[20:23]
	v_mfma_f32_16x16x32_bf16 v[12:15], v[168:171], v[214:217], v[12:15]
	v_mfma_f32_16x16x32_bf16 v[8:11], v[176:179], v[214:217], v[8:11]
	v_mfma_f32_16x16x32_bf16 v[4:7], v[168:171], v[222:225], v[4:7]
	v_mfma_f32_16x16x32_bf16 v[0:3], v[176:179], v[222:225], v[0:3]
	s_setprio 0
	s_barrier
	s_add_u32 s55, s55, 0x100
	s_addc_u32 s56, s56, 0
	s_cmp_ge_u32 s57, s53
	s_mov_b64 s[24:25], s[26:27]
	s_mov_b32 s28, s57
	s_cbranch_scc0 .LBB0_1246
	s_and_b64 vcc, exec, s[12:13]
	s_cbranch_vccz .LBB0_1251
	s_barrier
	s_cmp_lt_i32 s2, 0
	s_mov_b64 s[24:25], -1
	s_cbranch_scc1 .LBB0_1252
